# attention loops: PV waits thinned to one per MFMA pair, duplicate vmcnt waits and 0+x adds removed
# baseline (speedup 1.0000x reference)
; __device__ __forceinline__ void finishSM(f32x16& p0, f32x16& p1, float alpha, float& l_reg, bf16x8& pa0, bf16x8& pa1, bf16x8& pa2, bf16x8& pa3) {
; #pragma unroll
;   for (int r = 0; r < 16; ++r) p1[r] = __builtin_amdgcn_exp2f(p1[r]);
;   float ps = 0;
; #pragma unroll
;   for (int r = 0; r < 16; ++r) ps += p0[r];
; #pragma unroll
;   for (int r = 0; r < 16; ++r) ps += p1[r];
;   { auto rr = __builtin_amdgcn_permlane32_swap(__float_as_uint(ps), __float_as_uint(ps), false, false);
;     ps = __uint_as_float(rr[0]) + __uint_as_float(rr[1]); }
;   l_reg = l_reg * alpha + ps;
;     ...
;   PK4(p0, 0, pa0); PK4(p0, 8, pa1); PK4(p1, 0, pa2); PK4(p1, 8, pa3);
;     ...
; }
; template <int DK, bool QL>
; __device__ __forceinline__ void qkt(f32x16& p0, f32x16& p1, const bf16* Ks, const bf16x8* qr, const char* ql, int r32, int hi) {
;   p0 = f32x16{}; p1 = f32x16{};
; #pragma unroll
;   for (int d0 = 0; d0 < DK / 16; ++d0) { int cb = (d0 * 16 + hi * 8) * 2;
;     const bf16x8 qv = QL ? *reinterpret_cast<const bf16x8*>(ql + d0 * 1024) : qr[d0];
;     bf16x8 b0 = *reinterpret_cast<const bf16x8*>((const char*)Ks + kswz<DK>(r32, cb));
;     bf16x8 b1 = *reinterpret_cast<const bf16x8*>((const char*)Ks + kswz<DK>(32 + r32, cb));
;     p0 = __builtin_amdgcn_mfma_f32_32x32x16_bf16(b0, qv, p0, 0, 0, 0);
;     p1 = __builtin_amdgcn_mfma_f32_32x32x16_bf16(b1, qv, p1, 0, 0, 0); }
; }
.LBB0_660:
	ds_read_b128 v[66:69], v153
	ds_read_b128 v[70:73], v159 offset:49152
	ds_read_b128 v[74:77], v159 offset:57344
	ds_read_b128 v[218:221], v153 offset:1024
	ds_read_b128 v[222:225], v207 offset:49152
	ds_read_b128 v[226:229], v207 offset:57344
	v_add_f32_e32 v130, v216, v145
	s_waitcnt lgkmcnt(4)
	v_mfma_f32_32x32x16_bf16 v[82:97], v[70:73], v[66:69], 0
	v_add_f32_e32 v130, v131, v130
	v_add_f32_e32 v130, v215, v130
	v_add_f32_e32 v130, v132, v130
	v_add_f32_e32 v130, v144, v130
	v_add_f32_e32 v130, v133, v130
	v_add_f32_e32 v130, v143, v130
	v_add_f32_e32 v130, v140, v130
	s_waitcnt lgkmcnt(3)
	v_mfma_f32_32x32x16_bf16 v[66:81], v[74:77], v[66:69], 0
	v_add_f32_e32 v130, v142, v130
	v_add_f32_e32 v130, v139, v130
	v_add_f32_e32 v130, v141, v130
	v_exp_f32_e32 v126, v126
	v_add_f32_e32 v130, v136, v130
	v_exp_f32_e32 v127, v127
	v_add_f32_e32 v130, v138, v130
	s_waitcnt lgkmcnt(1)
	v_mfma_f32_32x32x16_bf16 v[82:97], v[222:225], v[218:221], v[82:97]
	v_exp_f32_e32 v124, v124
	v_add_f32_e32 v130, v135, v130
	v_exp_f32_e32 v125, v125
	v_add_f32_e32 v130, v137, v130
	v_exp_f32_e32 v118, v118
	v_add_f32_e32 v130, v126, v130
	v_exp_f32_e32 v119, v119
	s_waitcnt lgkmcnt(0)
	v_mfma_f32_32x32x16_bf16 v[66:81], v[226:229], v[218:221], v[66:81]
	ds_read_b128 v[218:221], v153 offset:2048
	ds_read_b128 v[222:225], v161 offset:49152
	ds_read_b128 v[226:229], v161 offset:57344
	v_add_f32_e32 v130, v127, v130
	v_exp_f32_e32 v116, v116
	v_add_f32_e32 v130, v124, v130
	v_exp_f32_e32 v117, v117
	v_add_f32_e32 v130, v125, v130
	v_exp_f32_e32 v114, v114
	s_waitcnt lgkmcnt(1)
	v_mfma_f32_32x32x16_bf16 v[82:97], v[222:225], v[218:221], v[82:97]
	v_add_f32_e32 v130, v118, v130
	v_exp_f32_e32 v115, v115
	v_add_f32_e32 v130, v119, v130
	v_exp_f32_e32 v128, v128
	v_add_f32_e32 v130, v116, v130
	v_exp_f32_e32 v129, v129
	v_add_f32_e32 v130, v117, v130
	s_waitcnt lgkmcnt(0)
	v_mfma_f32_32x32x16_bf16 v[66:81], v[226:229], v[218:221], v[66:81]
	ds_read_b128 v[218:221], v153 offset:3072
	ds_read_b128 v[222:225], v160 offset:49152
	ds_read_b128 v[226:229], v160 offset:57344
	v_exp_f32_e32 v122, v122
	v_add_f32_e32 v130, v114, v130
	v_exp_f32_e32 v123, v123
	v_add_f32_e32 v130, v115, v130
	v_exp_f32_e32 v120, v120
	v_add_f32_e32 v130, v128, v130
	s_waitcnt lgkmcnt(1)
	v_mfma_f32_32x32x16_bf16 v[82:97], v[222:225], v[218:221], v[82:97]
	v_exp_f32_e32 v121, v121
	v_add_f32_e32 v130, v129, v130
	v_add_f32_e32 v130, v122, v130
	v_add_f32_e32 v130, v123, v130
	v_add_f32_e32 v130, v120, v130
	v_add_f32_e32 v212, v121, v130
	v_mov_b32_e32 v213, v212
	s_waitcnt lgkmcnt(0)
	v_mfma_f32_32x32x16_bf16 v[66:81], v[226:229], v[218:221], v[66:81]
	ds_read_b128 v[218:221], v153 offset:4096
	ds_read_b128 v[222:225], v158 offset:49152
	ds_read_b128 v[226:229], v158 offset:57344
	v_permlane32_swap_b32_e32 v212, v213
	s_waitcnt lgkmcnt(1)
	v_mfma_f32_32x32x16_bf16 v[82:97], v[222:225], v[218:221], v[82:97]
	s_waitcnt lgkmcnt(0)
	v_mfma_f32_32x32x16_bf16 v[66:81], v[226:229], v[218:221], v[66:81]
	ds_read_b128 v[218:221], v153 offset:5120
	ds_read_b128 v[222:225], v156 offset:49152
	ds_read_b128 v[226:229], v156 offset:57344
	s_waitcnt lgkmcnt(1)
	v_mfma_f32_32x32x16_bf16 v[82:97], v[222:225], v[218:221], v[82:97]
	s_waitcnt lgkmcnt(0)
	v_mfma_f32_32x32x16_bf16 v[66:81], v[226:229], v[218:221], v[66:81]
	ds_read_b128 v[218:221], v153 offset:6144
	ds_read_b128 v[222:225], v157 offset:49152
	ds_read_b128 v[226:229], v157 offset:57344
	s_waitcnt lgkmcnt(1)
	v_mfma_f32_32x32x16_bf16 v[82:97], v[222:225], v[218:221], v[82:97]
	s_waitcnt lgkmcnt(0)
	v_mfma_f32_32x32x16_bf16 v[66:81], v[226:229], v[218:221], v[66:81]
	ds_read_b128 v[218:221], v153 offset:7168
	ds_read_b128 v[222:225], v176 offset:49152
	ds_read_b128 v[226:229], v176 offset:57344
	v_cvt_pk_bf16_f32 v130, v145, v216
	v_cvt_pk_bf16_f32 v131, v131, v215
	v_cvt_pk_bf16_f32 v132, v132, v144
	v_cvt_pk_bf16_f32 v133, v133, v143
	v_cvt_pk_bf16_f32 v140, v140, v142
	v_cvt_pk_bf16_f32 v141, v139, v141
	s_waitcnt lgkmcnt(1)
	v_mfma_f32_32x32x16_bf16 v[82:97], v[222:225], v[218:221], v[82:97]
	v_cvt_pk_bf16_f32 v142, v136, v138
	v_cvt_pk_bf16_f32 v143, v135, v137
	v_cvt_pk_bf16_f32 v136, v126, v127
	v_cvt_pk_bf16_f32 v137, v124, v125
	v_cvt_pk_bf16_f32 v138, v118, v119
	v_cvt_pk_bf16_f32 v139, v116, v117
	v_cvt_pk_bf16_f32 v214, v114, v115
	s_waitcnt lgkmcnt(0)
	v_mfma_f32_32x32x16_bf16 v[66:81], v[226:229], v[218:221], v[66:81]
	v_cvt_pk_bf16_f32 v215, v128, v129
	v_cvt_pk_bf16_f32 v216, v122, v123
	v_permlane32_swap_b32_e32 v130, v132
	v_cvt_pk_bf16_f32 v217, v120, v121
	v_permlane32_swap_b32_e32 v214, v216
	v_permlane32_swap_b32_e32 v131, v133
	v_permlane32_swap_b32_e32 v140, v142
	v_permlane32_swap_b32_e32 v141, v143
	v_permlane32_swap_b32_e32 v136, v138
	v_permlane32_swap_b32_e32 v137, v139
	v_permlane32_swap_b32_e32 v215, v217
	s_mov_b32 s2, 0xfff10000
	v_add_co_u32_e32 v118, vcc, s2, v146
	s_mov_b32 s2, 0xfff60000
	s_nop 0
	v_addc_co_u32_e32 v119, vcc, -1, v147, vcc
	v_add_co_u32_e32 v122, vcc, s2, v146
	s_nop 1
	v_addc_co_u32_e32 v123, vcc, -1, v147, vcc
	global_load_dwordx4 v[244:247], v[118:119], off
	s_nop 0
	global_load_dwordx4 v[118:121], v[118:119], off offset:-512
	s_nop 0
	global_load_dwordx4 v[194:197], v[122:123], off
	s_nop 0
	global_load_dwordx4 v[122:125], v[122:123], off offset:-512
	ds_read_b64_tr_b16 v[218:219], v152 offset:0
	ds_read_b64_tr_b16 v[220:221], v152 offset:0x800
	ds_read_b64_tr_b16 v[222:223], v152 offset:0x1000
	ds_read_b64_tr_b16 v[224:225], v152 offset:0x1800
	ds_read_b64_tr_b16 v[226:227], v152 offset:0x2000
	ds_read_b64_tr_b16 v[228:229], v152 offset:0x2800
	ds_read_b64_tr_b16 v[230:231], v152 offset:0x3000
	ds_read_b64_tr_b16 v[232:233], v152 offset:0x3800
	s_waitcnt lgkmcnt(4)
; #define SBAR() __builtin_amdgcn_sched_barrier(0)
; __device__ __forceinline__ void partialSM(f32x16& p0, f32x16& p1, float& m_reg, float& mn, float& alpha, float C, float thrRaw) {
;   float pmax = p0[0];
; #pragma unroll
;   for (int r = 1; r < 16; ++r) pmax = fmaxf(pmax, p0[r]);
; #pragma unroll
;   for (int r = 0; r < 16; ++r) pmax = fmaxf(pmax, p1[r]);
;   { auto rr = __builtin_amdgcn_permlane32_swap(__float_as_uint(pmax), __float_as_uint(pmax), false, false);
;     pmax = fmaxf(__uint_as_float(rr[0]), __uint_as_float(rr[1])); }
;   if (__builtin_expect(__all(pmax - m_reg <= thrRaw), 1)) { mn = m_reg; alpha = 1.f; }
;   else { mn = fmaxf(m_reg, pmax); alpha = __builtin_amdgcn_exp2f((m_reg - mn) * C); m_reg = mn; }
; template <int D0> __device__ __forceinline__ void pv_one(f32x16& od, int vb, bf16x8 pa0, bf16x8 pa1, bf16x8 pa2, bf16x8 pa3) {
;   const s16x4 l0 = tr_read<v_rd_off(D0, 0, 0)>(vb), h0 = tr_read<v_rd_off(D0, 0, 1)>(vb), l1 = tr_read<v_rd_off(D0, 1, 0)>(vb), h1 = tr_read<v_rd_off(D0, 1, 1)>(vb);
;   const s16x4 l2 = tr_read<v_rd_off(D0, 2, 0)>(vb), h2 = tr_read<v_rd_off(D0, 2, 1)>(vb), l3 = tr_read<v_rd_off(D0, 3, 0)>(vb), h3 = tr_read<v_rd_off(D0, 3, 1)>(vb);
;   asm volatile("s_waitcnt lgkmcnt(0)" ::: "memory"); SBAR();
;     ...
;   od = __builtin_amdgcn_mfma_f32_32x32x16_bf16(pa0, PK(l0, h0), od, 0, 0, 0);
;   od = __builtin_amdgcn_mfma_f32_32x32x16_bf16(pa1, PK(l1, h1), od, 0, 0, 0);
;   od = __builtin_amdgcn_mfma_f32_32x32x16_bf16(pa2, PK(l2, h2), od, 0, 0, 0);
;   od = __builtin_amdgcn_mfma_f32_32x32x16_bf16(pa3, PK(l3, h3), od, 0, 0, 0);
;     ...
; }
; __device__ __forceinline__ void pv_d0(f32x16* o, int vb, bf16x8 pa0, bf16x8 pa1, bf16x8 pa2, bf16x8 pa3) {
;   pv_one<0>(o[0], vb, pa0, pa1, pa2, pa3); pv_one<1>(o[1], vb, pa0, pa1, pa2, pa3); pv_one<2>(o[2], vb, pa0, pa1, pa2, pa3); pv_one<3>(o[3], vb, pa0, pa1, pa2, pa3);
	s_nop 0
	v_mfma_f32_32x32x16_bf16 v[18:33], v[130:133], v[218:221], v[18:33]
	ds_read_b64_tr_b16 v[218:219], v152 offset:0x200
	ds_read_b64_tr_b16 v[220:221], v152 offset:0xa00
	v_mfma_f32_32x32x16_bf16 v[18:33], v[140:143], v[222:225], v[18:33]
	ds_read_b64_tr_b16 v[222:223], v152 offset:0x1200
	ds_read_b64_tr_b16 v[224:225], v152 offset:0x1a00
	s_waitcnt lgkmcnt(4)
	v_mfma_f32_32x32x16_bf16 v[18:33], v[136:139], v[226:229], v[18:33]
	ds_read_b64_tr_b16 v[226:227], v152 offset:0x2200
	ds_read_b64_tr_b16 v[228:229], v152 offset:0x2a00
	v_mfma_f32_32x32x16_bf16 v[18:33], v[214:217], v[230:233], v[18:33]
	ds_read_b64_tr_b16 v[230:231], v152 offset:0x3200
	ds_read_b64_tr_b16 v[232:233], v152 offset:0x3a00
	s_waitcnt lgkmcnt(4)
	v_mfma_f32_32x32x16_bf16 v[50:65], v[130:133], v[218:221], v[50:65]
	ds_read_b64_tr_b16 v[218:219], v152 offset:0x400
	ds_read_b64_tr_b16 v[220:221], v152 offset:0xc00
	v_mfma_f32_32x32x16_bf16 v[50:65], v[140:143], v[222:225], v[50:65]
	ds_read_b64_tr_b16 v[222:223], v152 offset:0x1400
	ds_read_b64_tr_b16 v[224:225], v152 offset:0x1c00
	s_waitcnt lgkmcnt(4)
	v_mfma_f32_32x32x16_bf16 v[50:65], v[136:139], v[226:229], v[50:65]
	ds_read_b64_tr_b16 v[226:227], v152 offset:0x2400
	ds_read_b64_tr_b16 v[228:229], v152 offset:0x2c00
	v_mfma_f32_32x32x16_bf16 v[50:65], v[214:217], v[230:233], v[50:65]
	ds_read_b64_tr_b16 v[230:231], v152 offset:0x3400
	ds_read_b64_tr_b16 v[232:233], v152 offset:0x3c00
	s_waitcnt lgkmcnt(4)
	v_mfma_f32_32x32x16_bf16 v[2:17], v[130:133], v[218:221], v[2:17]
	ds_read_b64_tr_b16 v[218:219], v152 offset:0x600
	ds_read_b64_tr_b16 v[220:221], v152 offset:0xe00
	v_mfma_f32_32x32x16_bf16 v[2:17], v[140:143], v[222:225], v[2:17]
	ds_read_b64_tr_b16 v[222:223], v152 offset:0x1600
	ds_read_b64_tr_b16 v[224:225], v152 offset:0x1e00
	s_waitcnt lgkmcnt(4)
	v_mfma_f32_32x32x16_bf16 v[2:17], v[136:139], v[226:229], v[2:17]
	ds_read_b64_tr_b16 v[226:227], v152 offset:0x2600
	ds_read_b64_tr_b16 v[228:229], v152 offset:0x2e00
	v_mfma_f32_32x32x16_bf16 v[2:17], v[214:217], v[230:233], v[2:17]
	ds_read_b64_tr_b16 v[230:231], v152 offset:0x3600
	ds_read_b64_tr_b16 v[232:233], v152 offset:0x3e00
	s_waitcnt lgkmcnt(6)
	v_mfma_f32_32x32x16_bf16 v[34:49], v[130:133], v[218:221], v[34:49]
	v_max_f32_e32 v130, v83, v82
	v_max3_f32 v130, v130, v84, v85
	v_max3_f32 v130, v130, v86, v87
	v_max3_f32 v130, v130, v88, v89
	v_max3_f32 v130, v130, v90, v91
	v_max3_f32 v130, v130, v92, v93
	v_max3_f32 v130, v130, v94, v95
	s_waitcnt lgkmcnt(4)
	v_mfma_f32_32x32x16_bf16 v[34:49], v[140:143], v[222:225], v[34:49]
	v_max3_f32 v130, v130, v96, v97
	v_max3_f32 v130, v130, v66, v67
	v_max3_f32 v130, v130, v68, v69
	v_max3_f32 v130, v130, v70, v71
	v_max3_f32 v130, v130, v72, v73
	v_max3_f32 v130, v130, v74, v75
	v_max3_f32 v130, v130, v76, v77
	v_max3_f32 v130, v130, v78, v79
	s_waitcnt lgkmcnt(2)
	v_mfma_f32_32x32x16_bf16 v[34:49], v[136:139], v[226:229], v[34:49]
	v_max3_f32 v130, v130, v80, v81
	v_mov_b32_e32 v131, v130
	s_nop 1
	v_permlane32_swap_b32_e32 v130, v131
	v_max_f32_e32 v130, v131, v130
	v_sub_f32_e32 v131, v130, v134
	s_mov_b32 s2, 0x42b504f3
	v_cmp_ge_f32_e32 vcc, s2, v131
	v_max_f32_e32 v130, v134, v130
	s_waitcnt lgkmcnt(0)
	v_mfma_f32_32x32x16_bf16 v[34:49], v[214:217], v[230:233], v[34:49]
	v_sub_f32_e32 v131, v134, v130
	v_mul_f32_e32 v131, 0x3e0293ee, v131
	v_exp_f32_e32 v131, v131
	s_cmp_eq_u64 vcc, exec
	s_cselect_b64 s[2:3], -1, 0
	s_waitcnt vmcnt(4)
	v_cndmask_b32_e64 v214, v131, 1.0, s[2:3]
	v_cmp_gt_f32_e32 vcc, 1.0, v214
	s_waitcnt vmcnt(4)
	ds_write_b128 v177, v[98:101] offset:32768
	ds_write_b128 v208, v[102:105] offset:32768
	s_cbranch_vccz .LBB0_664
	s_and_saveexec_b64 s[4:5], s[0:1]
	ds_write_b32 v149, v214 offset:128
	s_or_b64 exec, exec, s[4:5]
	s_waitcnt lgkmcnt(0)
	v_add_u32_e32 v131, v148, v0
	ds_read_b128 v[136:139], v131 offset:128
	ds_read_b128 v[140:143], v131 offset:160
	ds_read_b128 v[216:219], v131 offset:192
	ds_read_b128 v[220:223], v131 offset:224
	s_waitcnt lgkmcnt(3)
	v_pk_mul_f32 v[50:51], v[136:137], v[50:51]
	v_pk_mul_f32 v[52:53], v[52:53], v[138:139]
	s_waitcnt lgkmcnt(2)
	v_pk_mul_f32 v[54:55], v[54:55], v[140:141]
	v_pk_mul_f32 v[56:57], v[56:57], v[142:143]
	s_waitcnt lgkmcnt(1)
	v_pk_mul_f32 v[58:59], v[58:59], v[216:217]
	v_pk_mul_f32 v[60:61], v[60:61], v[218:219]
	s_waitcnt lgkmcnt(0)
	v_pk_mul_f32 v[62:63], v[62:63], v[220:221]
	v_pk_mul_f32 v[30:31], v[30:31], v[220:221]
	v_pk_mul_f32 v[26:27], v[26:27], v[216:217]
	v_pk_mul_f32 v[22:23], v[22:23], v[140:141]
	v_pk_mul_f32 v[32:33], v[32:33], v[222:223]
	v_pk_mul_f32 v[28:29], v[28:29], v[218:219]
	v_pk_mul_f32 v[24:25], v[24:25], v[142:143]
	v_pk_mul_f32 v[20:21], v[20:21], v[138:139]
	v_pk_mul_f32 v[18:19], v[18:19], v[136:137]
	v_pk_mul_f32 v[64:65], v[64:65], v[222:223]
	v_pk_mul_f32 v[34:35], v[136:137], v[34:35]
	v_pk_mul_f32 v[36:37], v[36:37], v[138:139]
	v_pk_mul_f32 v[38:39], v[38:39], v[140:141]
	v_pk_mul_f32 v[40:41], v[40:41], v[142:143]
	v_pk_mul_f32 v[42:43], v[42:43], v[216:217]
	v_pk_mul_f32 v[44:45], v[44:45], v[218:219]
	v_pk_mul_f32 v[46:47], v[46:47], v[220:221]
	v_pk_mul_f32 v[14:15], v[14:15], v[220:221]
	v_pk_mul_f32 v[10:11], v[10:11], v[216:217]
	v_pk_mul_f32 v[6:7], v[6:7], v[140:141]
	v_pk_mul_f32 v[16:17], v[16:17], v[222:223]
	v_pk_mul_f32 v[12:13], v[12:13], v[218:219]
	v_pk_mul_f32 v[8:9], v[8:9], v[142:143]
	v_pk_mul_f32 v[4:5], v[4:5], v[138:139]
	v_pk_mul_f32 v[2:3], v[2:3], v[136:137]
	v_pk_mul_f32 v[48:49], v[48:49], v[222:223]
; __device__ __forceinline__ void partialSM(f32x16& p0, f32x16& p1, float& m_reg, float& mn, float& alpha, float C, float thrRaw) {
;     ...
;   float mnC = -mn * C;
; #pragma unroll
;   for (int r = 0; r < 16; ++r) p0[r] = fmaf(p0[r], C, mnC);
; #pragma unroll
;   for (int r = 0; r < 16; ++r) p1[r] = fmaf(p1[r], C, mnC);
; #pragma unroll
;   for (int r = 0; r < 16; ++r) p0[r] = __builtin_amdgcn_exp2f(p0[r]);
; }
; __device__ __forceinline__ void finishSM(f32x16& p0, f32x16& p1, float alpha, float& l_reg, bf16x8& pa0, bf16x8& pa1, bf16x8& pa2, bf16x8& pa3) {
; #pragma unroll
;   for (int r = 0; r < 16; ++r) p1[r] = __builtin_amdgcn_exp2f(p1[r]);
;   float ps = 0;
; #pragma unroll
;   for (int r = 0; r < 16; ++r) ps += p0[r];
; #pragma unroll
;   for (int r = 0; r < 16; ++r) ps += p1[r];
;   { auto rr = __builtin_amdgcn_permlane32_swap(__float_as_uint(ps), __float_as_uint(ps), false, false);
;     ps = __uint_as_float(rr[0]) + __uint_as_float(rr[1]); }
;   l_reg = l_reg * alpha + ps;
;     ...
;   PK4(p0, 0, pa0); PK4(p0, 8, pa1); PK4(p1, 0, pa2); PK4(p1, 8, pa3);
;     ...
; }
; template <int DK, bool QL>
; __device__ __forceinline__ void qkt(f32x16& p0, f32x16& p1, const bf16* Ks, const bf16x8* qr, const char* ql, int r32, int hi) {
;   p0 = f32x16{}; p1 = f32x16{};
; #pragma unroll
;   for (int d0 = 0; d0 < DK / 16; ++d0) { int cb = (d0 * 16 + hi * 8) * 2;
;     const bf16x8 qv = QL ? *reinterpret_cast<const bf16x8*>(ql + d0 * 1024) : qr[d0];
;     bf16x8 b0 = *reinterpret_cast<const bf16x8*>((const char*)Ks + kswz<DK>(r32, cb));
;     bf16x8 b1 = *reinterpret_cast<const bf16x8*>((const char*)Ks + kswz<DK>(32 + r32, cb));
;     p0 = __builtin_amdgcn_mfma_f32_32x32x16_bf16(b0, qv, p0, 0, 0, 0);
;     p1 = __builtin_amdgcn_mfma_f32_32x32x16_bf16(b1, qv, p1, 0, 0, 0); }
.LBB0_664:
	v_cndmask_b32_e64 v215, v130, v134, s[2:3]
	v_mul_f32_e32 v216, 0xbe0293ee, v215
	v_fmamk_f32 v82, v82, 0x3e0293ee, v216
	v_fmamk_f32 v83, v83, 0x3e0293ee, v216
	v_fmamk_f32 v84, v84, 0x3e0293ee, v216
	v_fmamk_f32 v85, v85, 0x3e0293ee, v216
	v_fmamk_f32 v86, v86, 0x3e0293ee, v216
	v_fmamk_f32 v87, v87, 0x3e0293ee, v216
	v_fmamk_f32 v88, v88, 0x3e0293ee, v216
	v_fmamk_f32 v89, v89, 0x3e0293ee, v216
	v_fmamk_f32 v90, v90, 0x3e0293ee, v216
	v_fmamk_f32 v91, v91, 0x3e0293ee, v216
	v_fmamk_f32 v92, v92, 0x3e0293ee, v216
	v_fmamk_f32 v93, v93, 0x3e0293ee, v216
	v_fmamk_f32 v94, v94, 0x3e0293ee, v216
	v_fmamk_f32 v95, v95, 0x3e0293ee, v216
	v_fmamk_f32 v96, v96, 0x3e0293ee, v216
	v_fmamk_f32 v97, v97, 0x3e0293ee, v216
	v_exp_f32_e32 v130, v82
	v_exp_f32_e32 v145, v83
	v_exp_f32_e32 v131, v84
	v_exp_f32_e32 v144, v85
	v_exp_f32_e32 v132, v86
	v_exp_f32_e32 v143, v87
	v_exp_f32_e32 v133, v88
	v_exp_f32_e32 v142, v89
	v_exp_f32_e32 v134, v90
	v_exp_f32_e32 v141, v91
	v_exp_f32_e32 v135, v92
	v_exp_f32_e32 v140, v93
	v_exp_f32_e32 v136, v94
	v_exp_f32_e32 v139, v95
	v_exp_f32_e32 v137, v96
	v_exp_f32_e32 v138, v97
	v_fmamk_f32 v218, v71, 0x3e0293ee, v216
	v_fmamk_f32 v217, v78, 0x3e0293ee, v216
	s_add_i32 s8, s8, 2
	v_fmamk_f32 v225, v66, 0x3e0293ee, v216
	v_fmamk_f32 v226, v67, 0x3e0293ee, v216
	v_fmamk_f32 v227, v68, 0x3e0293ee, v216
	v_fmamk_f32 v228, v69, 0x3e0293ee, v216
	v_fmamk_f32 v229, v70, 0x3e0293ee, v216
	v_fmamk_f32 v219, v72, 0x3e0293ee, v216
	v_fmamk_f32 v220, v73, 0x3e0293ee, v216
	v_fmamk_f32 v221, v74, 0x3e0293ee, v216
	v_fmamk_f32 v222, v75, 0x3e0293ee, v216
	v_fmamk_f32 v223, v76, 0x3e0293ee, v216
	v_fmamk_f32 v224, v77, 0x3e0293ee, v216
	v_fmamk_f32 v230, v79, 0x3e0293ee, v216
	v_fmamk_f32 v231, v80, 0x3e0293ee, v216
	v_fmac_f32_e32 v216, 0x3e0293ee, v81
	s_waitcnt lgkmcnt(0)
	s_barrier
	ds_write_b128 v209, v[106:109]
	ds_write_b128 v210, v[110:113]
	ds_read_b128 v[66:69], v153
	ds_read_b128 v[70:73], v159 offset:32768
	ds_read_b128 v[74:77], v159 offset:40960
	ds_read_b128 v[232:235], v153 offset:1024
	ds_read_b128 v[236:239], v207 offset:32768
	ds_read_b128 v[240:243], v207 offset:40960
	v_exp_f32_e32 v174, v219
	v_exp_f32_e32 v219, v221
	s_waitcnt lgkmcnt(4)
	v_mfma_f32_32x32x16_bf16 v[82:97], v[70:73], v[66:69], 0
	v_exp_f32_e32 v221, v223
	v_exp_f32_e32 v223, v217
	v_add_f32_e32 v217, v145, v130
	v_add_f32_e32 v217, v131, v217
	v_add_f32_e32 v217, v144, v217
	v_add_f32_e32 v217, v132, v217
	s_waitcnt lgkmcnt(3)
	v_mfma_f32_32x32x16_bf16 v[66:81], v[74:77], v[66:69], 0
	v_add_f32_e32 v217, v143, v217
	v_add_f32_e32 v217, v133, v217
	v_add_f32_e32 v217, v142, v217
	v_add_f32_e32 v217, v134, v217
	v_add_f32_e32 v217, v141, v217
	v_add_f32_e32 v217, v135, v217
	v_add_f32_e32 v217, v140, v217
	s_waitcnt lgkmcnt(1)
	v_mfma_f32_32x32x16_bf16 v[82:97], v[236:239], v[232:235], v[82:97]
	v_exp_f32_e32 v164, v225
	v_add_f32_e32 v217, v136, v217
	v_exp_f32_e32 v165, v226
	v_add_f32_e32 v217, v139, v217
	v_exp_f32_e32 v166, v227
	v_add_f32_e32 v217, v137, v217
	v_exp_f32_e32 v167, v228
	s_waitcnt lgkmcnt(0)
	v_mfma_f32_32x32x16_bf16 v[66:81], v[240:243], v[232:235], v[66:81]
	ds_read_b128 v[232:235], v153 offset:2048
	ds_read_b128 v[236:239], v161 offset:32768
	ds_read_b128 v[240:243], v161 offset:40960
	v_add_f32_e32 v217, v138, v217
	v_exp_f32_e32 v172, v229
	v_add_f32_e32 v217, v164, v217
	v_exp_f32_e32 v173, v218
	v_add_f32_e32 v217, v165, v217
	v_add_f32_e32 v217, v166, v217
	s_waitcnt lgkmcnt(1)
	v_mfma_f32_32x32x16_bf16 v[82:97], v[236:239], v[232:235], v[82:97]
	v_exp_f32_e32 v175, v220
	v_add_f32_e32 v217, v167, v217
	v_add_f32_e32 v217, v172, v217
	v_exp_f32_e32 v220, v222
	v_add_f32_e32 v217, v173, v217
	v_add_f32_e32 v217, v174, v217
	v_exp_f32_e32 v222, v224
	s_waitcnt lgkmcnt(0)
	v_mfma_f32_32x32x16_bf16 v[66:81], v[240:243], v[232:235], v[66:81]
	ds_read_b128 v[232:235], v153 offset:3072
	ds_read_b128 v[236:239], v160 offset:32768
	ds_read_b128 v[240:243], v160 offset:40960
	v_add_f32_e32 v217, v175, v217
	v_add_f32_e32 v217, v219, v217
	v_exp_f32_e32 v224, v230
	v_add_f32_e32 v217, v220, v217
	v_exp_f32_e32 v225, v231
	v_add_f32_e32 v217, v221, v217
	s_waitcnt lgkmcnt(1)
	v_mfma_f32_32x32x16_bf16 v[82:97], v[236:239], v[232:235], v[82:97]
	v_exp_f32_e32 v216, v216
	v_add_f32_e32 v217, v222, v217
	v_add_f32_e32 v217, v223, v217
	v_add_f32_e32 v217, v224, v217
	v_add_f32_e32 v217, v225, v217
	v_add_f32_e32 v217, v216, v217
	v_mov_b32_e32 v218, v217
	s_waitcnt lgkmcnt(0)
	v_mfma_f32_32x32x16_bf16 v[66:81], v[240:243], v[232:235], v[66:81]
	ds_read_b128 v[232:235], v153 offset:4096
	ds_read_b128 v[236:239], v158 offset:32768
	ds_read_b128 v[240:243], v158 offset:40960
	v_permlane32_swap_b32_e32 v217, v218
	s_waitcnt lgkmcnt(1)
	v_mfma_f32_32x32x16_bf16 v[82:97], v[236:239], v[232:235], v[82:97]
	s_waitcnt lgkmcnt(0)
	v_mfma_f32_32x32x16_bf16 v[66:81], v[240:243], v[232:235], v[66:81]
	ds_read_b128 v[232:235], v153 offset:5120
	ds_read_b128 v[236:239], v156 offset:32768
	ds_read_b128 v[240:243], v156 offset:40960
	s_waitcnt lgkmcnt(1)
	v_mfma_f32_32x32x16_bf16 v[82:97], v[236:239], v[232:235], v[82:97]
	s_waitcnt lgkmcnt(0)
	v_mfma_f32_32x32x16_bf16 v[66:81], v[240:243], v[232:235], v[66:81]
	ds_read_b128 v[232:235], v153 offset:6144
	ds_read_b128 v[236:239], v157 offset:32768
	ds_read_b128 v[240:243], v157 offset:40960
	s_waitcnt lgkmcnt(1)
	v_mfma_f32_32x32x16_bf16 v[82:97], v[236:239], v[232:235], v[82:97]
	s_waitcnt lgkmcnt(0)
	v_mfma_f32_32x32x16_bf16 v[66:81], v[240:243], v[232:235], v[66:81]
	ds_read_b128 v[232:235], v153 offset:7168
	ds_read_b128 v[236:239], v176 offset:32768
	ds_read_b128 v[240:243], v176 offset:40960
	v_cvt_pk_bf16_f32 v130, v130, v145
	v_cvt_pk_bf16_f32 v131, v131, v144
	v_cvt_pk_bf16_f32 v132, v132, v143
	v_cvt_pk_bf16_f32 v133, v133, v142
	v_cvt_pk_bf16_f32 v134, v134, v141
	v_cvt_pk_bf16_f32 v135, v135, v140
	s_waitcnt lgkmcnt(1)
	v_mfma_f32_32x32x16_bf16 v[82:97], v[236:239], v[232:235], v[82:97]
	v_cvt_pk_bf16_f32 v136, v136, v139
	v_cvt_pk_bf16_f32 v137, v137, v138
	v_cvt_pk_bf16_f32 v138, v164, v165
	v_cvt_pk_bf16_f32 v139, v166, v167
	v_cvt_pk_bf16_f32 v140, v172, v173
	v_cvt_pk_bf16_f32 v141, v174, v175
	v_cvt_pk_bf16_f32 v142, v219, v220
	s_waitcnt lgkmcnt(0)
	v_mfma_f32_32x32x16_bf16 v[66:81], v[240:243], v[232:235], v[66:81]
	v_cvt_pk_bf16_f32 v143, v221, v222
	v_cvt_pk_bf16_f32 v144, v223, v224
	v_cvt_pk_bf16_f32 v145, v225, v216
	v_permlane32_swap_b32_e32 v130, v132
	v_permlane32_swap_b32_e32 v131, v133
	v_permlane32_swap_b32_e32 v134, v136
	v_permlane32_swap_b32_e32 v135, v137
	v_permlane32_swap_b32_e32 v138, v140
	v_permlane32_swap_b32_e32 v139, v141
	v_permlane32_swap_b32_e32 v142, v144
	v_permlane32_swap_b32_e32 v143, v145
	s_cmp_gt_u32 s8, 60
	s_cselect_b64 s[4:5], -1, 0
	s_and_b64 vcc, exec, s[4:5]
	s_cbranch_vccnz .Lod_gqa
; #define SBAR() __builtin_amdgcn_sched_barrier(0)
; #define SLOAD(i, k0) do { sr_[i].vs0 = *reinterpret_cast<const bf16x8*>(&Vh[(long)((k0) + sr) * LDP + sc]); sr_[i].vs1 = *reinterpret_cast<const bf16x8*>(&Vh[(long)((k0) + 32 + sr) * LDP + sc]); \
;     sr_[i].ks0 = *reinterpret_cast<const bf16x8*>(&Kh[(long)((k0) + ksr) * LDP + ksc]); if (DK == 128) sr_[i].ks1 = *reinterpret_cast<const bf16x8*>(&Kh[(long)((k0) + 32 + ksr) * LDP + ksc]); } while (0)
; #define SWAIT() do { if (SD == 1) asm volatile("s_waitcnt vmcnt(0)" ::: "memory"); else if (DK == 128) asm volatile("s_waitcnt vmcnt(4)" ::: "memory"); else asm volatile("s_waitcnt vmcnt(3)" ::: "memory"); } while (0)
; #define RESC(a) do { if (__any((a) < 1.f)) { if (hi == 0) al_l[r32] = (a); asm volatile("s_waitcnt lgkmcnt(0)" ::: "memory"); \
;     _Pragma("unroll") for (int d = 0; d < 4; ++d) _Pragma("unroll") for (int r = 0; r < 16; ++r) o[d][r] *= al_l[crow(r, hi)]; } } while (0)
; template <int D0> __device__ __forceinline__ void pv_one(f32x16& od, int vb, bf16x8 pa0, bf16x8 pa1, bf16x8 pa2, bf16x8 pa3) {
;   const s16x4 l0 = tr_read<v_rd_off(D0, 0, 0)>(vb), h0 = tr_read<v_rd_off(D0, 0, 1)>(vb), l1 = tr_read<v_rd_off(D0, 1, 0)>(vb), h1 = tr_read<v_rd_off(D0, 1, 1)>(vb);
;   const s16x4 l2 = tr_read<v_rd_off(D0, 2, 0)>(vb), h2 = tr_read<v_rd_off(D0, 2, 1)>(vb), l3 = tr_read<v_rd_off(D0, 3, 0)>(vb), h3 = tr_read<v_rd_off(D0, 3, 1)>(vb);
;   asm volatile("s_waitcnt lgkmcnt(0)" ::: "memory"); SBAR();
;     ...
;   od = __builtin_amdgcn_mfma_f32_32x32x16_bf16(pa0, PK(l0, h0), od, 0, 0, 0);
;   od = __builtin_amdgcn_mfma_f32_32x32x16_bf16(pa1, PK(l1, h1), od, 0, 0, 0);
;   od = __builtin_amdgcn_mfma_f32_32x32x16_bf16(pa2, PK(l2, h2), od, 0, 0, 0);
;   od = __builtin_amdgcn_mfma_f32_32x32x16_bf16(pa3, PK(l3, h3), od, 0, 0, 0);
;     ...
; }
; __device__ __forceinline__ void pv_d0(f32x16* o, int vb, bf16x8 pa0, bf16x8 pa1, bf16x8 pa2, bf16x8 pa3) {
;   pv_one<0>(o[0], vb, pa0, pa1, pa2, pa3); pv_one<1>(o[1], vb, pa0, pa1, pa2, pa3); pv_one<2>(o[2], vb, pa0, pa1, pa2, pa3); pv_one<3>(o[3], vb, pa0, pa1, pa2, pa3);
; template <int DK, bool NA, bool QL, int SD> ...
;     ...
;     if (SD == 1 || j + 3 < NT) SLOAD(SE, (j + 1 + SD) * KVBLK); SBAR();
;     pv_d0(o, vb0 + (int)SHM_V, pa0, pa1, pa2, pa3); partialSM(pA0, pA1, m_reg, mnA, alA, C, thrRaw);
;     __syncthreads(); SWAIT(); SWRITE(1, SO);
;     RESC(alA); __syncthreads();
	v_add_co_u32_e32 v98, vcc, 0xfffb0000, v146
	s_nop 1
	v_addc_co_u32_e32 v99, vcc, -1, v147, vcc
	global_load_dwordx4 v[106:109], v[98:99], off
	s_nop 0
	global_load_dwordx4 v[98:101], v[98:99], off offset:-512
	s_nop 0
	global_load_dwordx4 v[110:113], v[146:147], off
	global_load_dwordx4 v[102:105], v[146:147], off offset:-512
.LBB0_666:
	ds_read_b64_tr_b16 v[220:221], v151 offset:0
	ds_read_b64_tr_b16 v[222:223], v151 offset:0x800
	ds_read_b64_tr_b16 v[224:225], v151 offset:0x1000
	ds_read_b64_tr_b16 v[226:227], v151 offset:0x1800
	ds_read_b64_tr_b16 v[228:229], v151 offset:0x2000
	ds_read_b64_tr_b16 v[230:231], v151 offset:0x2800
	ds_read_b64_tr_b16 v[232:233], v151 offset:0x3000
	ds_read_b64_tr_b16 v[234:235], v151 offset:0x3800
	s_waitcnt lgkmcnt(4)
	s_nop 0
	v_mfma_f32_32x32x16_bf16 v[18:33], v[130:133], v[220:223], v[18:33]
	ds_read_b64_tr_b16 v[220:221], v151 offset:0x200
	ds_read_b64_tr_b16 v[222:223], v151 offset:0xa00
	v_mfma_f32_32x32x16_bf16 v[18:33], v[134:137], v[224:227], v[18:33]
	ds_read_b64_tr_b16 v[224:225], v151 offset:0x1200
	ds_read_b64_tr_b16 v[226:227], v151 offset:0x1a00
	s_waitcnt lgkmcnt(4)
	v_mfma_f32_32x32x16_bf16 v[18:33], v[138:141], v[228:231], v[18:33]
	ds_read_b64_tr_b16 v[228:229], v151 offset:0x2200
	ds_read_b64_tr_b16 v[230:231], v151 offset:0x2a00
	v_mfma_f32_32x32x16_bf16 v[18:33], v[142:145], v[232:235], v[18:33]
	ds_read_b64_tr_b16 v[232:233], v151 offset:0x3200
	ds_read_b64_tr_b16 v[234:235], v151 offset:0x3a00
	s_waitcnt lgkmcnt(4)
	v_mfma_f32_32x32x16_bf16 v[50:65], v[130:133], v[220:223], v[50:65]
	ds_read_b64_tr_b16 v[220:221], v151 offset:0x400
	ds_read_b64_tr_b16 v[222:223], v151 offset:0xc00
	v_mfma_f32_32x32x16_bf16 v[50:65], v[134:137], v[224:227], v[50:65]
	ds_read_b64_tr_b16 v[224:225], v151 offset:0x1400
	ds_read_b64_tr_b16 v[226:227], v151 offset:0x1c00
	s_waitcnt lgkmcnt(4)
	v_mfma_f32_32x32x16_bf16 v[50:65], v[138:141], v[228:231], v[50:65]
	ds_read_b64_tr_b16 v[228:229], v151 offset:0x2400
	ds_read_b64_tr_b16 v[230:231], v151 offset:0x2c00
	v_mfma_f32_32x32x16_bf16 v[50:65], v[142:145], v[232:235], v[50:65]
	ds_read_b64_tr_b16 v[232:233], v151 offset:0x3400
	ds_read_b64_tr_b16 v[234:235], v151 offset:0x3c00
	s_waitcnt lgkmcnt(4)
	v_mfma_f32_32x32x16_bf16 v[2:17], v[130:133], v[220:223], v[2:17]
	ds_read_b64_tr_b16 v[220:221], v151 offset:0x600
	ds_read_b64_tr_b16 v[222:223], v151 offset:0xe00
	v_mfma_f32_32x32x16_bf16 v[2:17], v[134:137], v[224:227], v[2:17]
	ds_read_b64_tr_b16 v[224:225], v151 offset:0x1600
	ds_read_b64_tr_b16 v[226:227], v151 offset:0x1e00
	s_waitcnt lgkmcnt(4)
	v_mfma_f32_32x32x16_bf16 v[2:17], v[138:141], v[228:231], v[2:17]
	ds_read_b64_tr_b16 v[228:229], v151 offset:0x2600
	ds_read_b64_tr_b16 v[230:231], v151 offset:0x2e00
	v_mfma_f32_32x32x16_bf16 v[2:17], v[142:145], v[232:235], v[2:17]
	ds_read_b64_tr_b16 v[232:233], v151 offset:0x3600
	ds_read_b64_tr_b16 v[234:235], v151 offset:0x3e00
	s_waitcnt lgkmcnt(6)
	v_mfma_f32_32x32x16_bf16 v[34:49], v[130:133], v[220:223], v[34:49]
	v_max_f32_e32 v130, v83, v82
	v_max3_f32 v130, v130, v84, v85
	v_max3_f32 v130, v130, v86, v87
	v_max3_f32 v130, v130, v88, v89
	v_max3_f32 v130, v130, v90, v91
	v_max3_f32 v130, v130, v92, v93
	v_max3_f32 v130, v130, v94, v95
	s_waitcnt lgkmcnt(4)
	v_mfma_f32_32x32x16_bf16 v[34:49], v[134:137], v[224:227], v[34:49]
	v_max3_f32 v130, v130, v96, v97
	v_max3_f32 v130, v130, v66, v67
	v_max3_f32 v130, v130, v68, v69
	v_max3_f32 v130, v130, v70, v71
	v_max3_f32 v130, v130, v72, v73
	v_max3_f32 v130, v130, v74, v75
	v_max3_f32 v130, v130, v76, v77
	v_max3_f32 v130, v130, v78, v79
	s_waitcnt lgkmcnt(2)
	v_mfma_f32_32x32x16_bf16 v[34:49], v[138:141], v[228:231], v[34:49]
	v_max3_f32 v130, v130, v80, v81
	v_mov_b32_e32 v131, v130
	s_nop 1
	v_permlane32_swap_b32_e32 v130, v131
	v_max_f32_e32 v130, v131, v130
	v_sub_f32_e32 v131, v130, v215
	s_mov_b32 s2, 0x42b504f3
	v_cmp_ge_f32_e32 vcc, s2, v131
	v_max_f32_e32 v131, v215, v130
	s_waitcnt lgkmcnt(0)
	v_mfma_f32_32x32x16_bf16 v[34:49], v[142:145], v[232:235], v[34:49]
	v_sub_f32_e32 v130, v215, v131
	v_mul_f32_e32 v130, 0x3e0293ee, v130
	v_exp_f32_e32 v130, v130
	s_cmp_eq_u64 vcc, exec
	s_cselect_b64 s[2:3], -1, 0
	s_waitcnt vmcnt(4)
	v_cndmask_b32_e64 v130, v130, 1.0, s[2:3]
	v_cmp_gt_f32_e32 vcc, 1.0, v130
	ds_write_b128 v177, v[118:121] offset:49152
	ds_write_b128 v208, v[122:125] offset:49152
	s_cbranch_vccz .LBB0_670
	s_and_saveexec_b64 s[6:7], s[0:1]
	ds_write_b32 v149, v130 offset:128
	s_or_b64 exec, exec, s[6:7]
	s_waitcnt lgkmcnt(0)
	v_add_u32_e32 v126, v148, v0
	ds_read_b128 v[114:117], v126 offset:128
	ds_read_b128 v[118:121], v126 offset:160
	ds_read_b128 v[122:125], v126 offset:192
	ds_read_b128 v[126:129], v126 offset:224
	s_waitcnt lgkmcnt(3)
	v_pk_mul_f32 v[50:51], v[114:115], v[50:51]
	v_pk_mul_f32 v[52:53], v[52:53], v[116:117]
	s_waitcnt lgkmcnt(2)
	v_pk_mul_f32 v[54:55], v[54:55], v[118:119]
	v_pk_mul_f32 v[56:57], v[56:57], v[120:121]
	s_waitcnt lgkmcnt(1)
	v_pk_mul_f32 v[58:59], v[58:59], v[122:123]
	v_pk_mul_f32 v[60:61], v[60:61], v[124:125]
	s_waitcnt lgkmcnt(0)
	v_pk_mul_f32 v[62:63], v[62:63], v[126:127]
	v_pk_mul_f32 v[30:31], v[30:31], v[126:127]
	v_pk_mul_f32 v[26:27], v[26:27], v[122:123]
	v_pk_mul_f32 v[22:23], v[22:23], v[118:119]
	v_pk_mul_f32 v[32:33], v[32:33], v[128:129]
	v_pk_mul_f32 v[28:29], v[28:29], v[124:125]
	v_pk_mul_f32 v[24:25], v[24:25], v[120:121]
	v_pk_mul_f32 v[20:21], v[20:21], v[116:117]
	v_pk_mul_f32 v[18:19], v[18:19], v[114:115]
	v_pk_mul_f32 v[64:65], v[64:65], v[128:129]
	v_pk_mul_f32 v[34:35], v[114:115], v[34:35]
	v_pk_mul_f32 v[36:37], v[36:37], v[116:117]
	v_pk_mul_f32 v[38:39], v[38:39], v[118:119]
	v_pk_mul_f32 v[40:41], v[40:41], v[120:121]
	v_pk_mul_f32 v[42:43], v[42:43], v[122:123]
	v_pk_mul_f32 v[44:45], v[44:45], v[124:125]
	v_pk_mul_f32 v[46:47], v[46:47], v[126:127]
	v_pk_mul_f32 v[14:15], v[14:15], v[126:127]
	v_pk_mul_f32 v[10:11], v[10:11], v[122:123]
	v_pk_mul_f32 v[6:7], v[6:7], v[118:119]
	v_pk_mul_f32 v[16:17], v[16:17], v[128:129]
	v_pk_mul_f32 v[12:13], v[12:13], v[124:125]
	v_pk_mul_f32 v[8:9], v[8:9], v[120:121]
	v_pk_mul_f32 v[4:5], v[4:5], v[116:117]
	v_pk_mul_f32 v[2:3], v[2:3], v[114:115]
	v_pk_mul_f32 v[48:49], v[48:49], v[128:129]

; #define SBAR() __builtin_amdgcn_sched_barrier(0)
; __device__ __forceinline__ void finishSM(f32x16& p0, f32x16& p1, float alpha, float& l_reg, bf16x8& pa0, bf16x8& pa1, bf16x8& pa2, bf16x8& pa3) {
; #pragma unroll
;   for (int r = 0; r < 16; ++r) p1[r] = __builtin_amdgcn_exp2f(p1[r]);
;   float ps = 0;
; #pragma unroll
;   for (int r = 0; r < 16; ++r) ps += p0[r];
; #pragma unroll
;   for (int r = 0; r < 16; ++r) ps += p1[r];
;   { auto rr = __builtin_amdgcn_permlane32_swap(__float_as_uint(ps), __float_as_uint(ps), false, false);
;     ps = __uint_as_float(rr[0]) + __uint_as_float(rr[1]); }
;   l_reg = l_reg * alpha + ps;
;     ...
;   PK4(p0, 0, pa0); PK4(p0, 8, pa1); PK4(p1, 0, pa2); PK4(p1, 8, pa3);
;     ...
; }
; template <int DK, bool QL>
; __device__ __forceinline__ void qkt(f32x16& p0, f32x16& p1, const bf16* Ks, const bf16x8* qr, const char* ql, int r32, int hi) {
;   p0 = f32x16{}; p1 = f32x16{};
; #pragma unroll
;   for (int d0 = 0; d0 < DK / 16; ++d0) { int cb = (d0 * 16 + hi * 8) * 2;
;     const bf16x8 qv = QL ? *reinterpret_cast<const bf16x8*>(ql + d0 * 1024) : qr[d0];
;     bf16x8 b0 = *reinterpret_cast<const bf16x8*>((const char*)Ks + kswz<DK>(r32, cb));
;     bf16x8 b1 = *reinterpret_cast<const bf16x8*>((const char*)Ks + kswz<DK>(32 + r32, cb));
;     p0 = __builtin_amdgcn_mfma_f32_32x32x16_bf16(b0, qv, p0, 0, 0, 0);
;     p1 = __builtin_amdgcn_mfma_f32_32x32x16_bf16(b1, qv, p1, 0, 0, 0); }
; template <int D0> __device__ __forceinline__ void pv_one(f32x16& od, int vb, bf16x8 pa0, bf16x8 pa1, bf16x8 pa2, bf16x8 pa3) {
;   const s16x4 l0 = tr_read<v_rd_off(D0, 0, 0)>(vb), h0 = tr_read<v_rd_off(D0, 0, 1)>(vb), l1 = tr_read<v_rd_off(D0, 1, 0)>(vb), h1 = tr_read<v_rd_off(D0, 1, 1)>(vb);
;   const s16x4 l2 = tr_read<v_rd_off(D0, 2, 0)>(vb), h2 = tr_read<v_rd_off(D0, 2, 1)>(vb), l3 = tr_read<v_rd_off(D0, 3, 0)>(vb), h3 = tr_read<v_rd_off(D0, 3, 1)>(vb);
;   asm volatile("s_waitcnt lgkmcnt(0)" ::: "memory"); SBAR();
;     ...
;   od = __builtin_amdgcn_mfma_f32_32x32x16_bf16(pa0, PK(l0, h0), od, 0, 0, 0);
;   od = __builtin_amdgcn_mfma_f32_32x32x16_bf16(pa1, PK(l1, h1), od, 0, 0, 0);
;   od = __builtin_amdgcn_mfma_f32_32x32x16_bf16(pa2, PK(l2, h2), od, 0, 0, 0);
;   od = __builtin_amdgcn_mfma_f32_32x32x16_bf16(pa3, PK(l3, h3), od, 0, 0, 0);
;     ...
; }
; __device__ __forceinline__ void pv_d0(f32x16* o, int vb, bf16x8 pa0, bf16x8 pa1, bf16x8 pa2, bf16x8 pa3) {
.LBB0_682:
	ds_read_b128 v[66:69], v212 offset:49152
	ds_read_b128 v[70:73], v212 offset:53248
	v_exp_f32_e32 v143, v138
	v_add_f32_e32 v138, v226, v177
	s_waitcnt lgkmcnt(1)
	v_mfma_f32_32x32x16_bf16 v[82:97], v[66:69], v[110:113], 0
	v_add_f32_e32 v138, v161, v138
	v_add_f32_e32 v138, v223, v138
	v_add_f32_e32 v138, v153, v138
	ds_read_b128 v[228:231], v216 offset:49152
	ds_read_b128 v[232:235], v216 offset:53248
	v_add_f32_e32 v138, v176, v138
	v_add_f32_e32 v138, v152, v138
	v_add_f32_e32 v138, v160, v138
	s_waitcnt lgkmcnt(2)
	v_mfma_f32_32x32x16_bf16 v[66:81], v[70:73], v[110:113], 0
	v_add_f32_e32 v138, v149, v138
	v_add_f32_e32 v138, v151, v138
	v_add_f32_e32 v138, v147, v138
	v_add_f32_e32 v138, v150, v138
	v_add_f32_e32 v138, v145, v138
	v_exp_f32_e32 v164, v139
	v_add_f32_e32 v138, v148, v138
	s_waitcnt lgkmcnt(1)
	v_mfma_f32_32x32x16_bf16 v[82:97], v[228:231], v[106:109], v[82:97]
	v_exp_f32_e32 v136, v136
	v_add_f32_e32 v138, v144, v138
	v_exp_f32_e32 v137, v137
	v_add_f32_e32 v138, v146, v138
	v_exp_f32_e32 v130, v130
	v_add_f32_e32 v138, v143, v138
	v_exp_f32_e32 v131, v131
	s_waitcnt lgkmcnt(0)
	v_mfma_f32_32x32x16_bf16 v[66:81], v[232:235], v[106:109], v[66:81]
	ds_read_b128 v[228:231], v217 offset:49152
	ds_read_b128 v[232:235], v217 offset:53248
	v_add_f32_e32 v138, v164, v138
	v_exp_f32_e32 v128, v128
	v_add_f32_e32 v138, v136, v138
	v_exp_f32_e32 v129, v129
	v_add_f32_e32 v138, v137, v138
	v_exp_f32_e32 v126, v126
	s_waitcnt lgkmcnt(1)
	v_mfma_f32_32x32x16_bf16 v[82:97], v[228:231], v[98:101], v[82:97]
	v_add_f32_e32 v138, v130, v138
	v_exp_f32_e32 v127, v127
	v_add_f32_e32 v138, v131, v138
	v_exp_f32_e32 v165, v140
	v_add_f32_e32 v138, v128, v138
	v_exp_f32_e32 v166, v141
	v_add_f32_e32 v138, v129, v138
	s_waitcnt lgkmcnt(0)
	v_mfma_f32_32x32x16_bf16 v[66:81], v[232:235], v[98:101], v[66:81]
	ds_read_b128 v[228:231], v218 offset:49152
	ds_read_b128 v[232:235], v218 offset:53248
	v_exp_f32_e32 v134, v134
	v_add_f32_e32 v138, v126, v138
	v_exp_f32_e32 v135, v135
	v_add_f32_e32 v138, v127, v138
	v_exp_f32_e32 v132, v132
	v_add_f32_e32 v138, v165, v138
	s_waitcnt lgkmcnt(1)
	v_mfma_f32_32x32x16_bf16 v[82:97], v[228:231], v[102:105], v[82:97]
	v_exp_f32_e32 v133, v133
	v_add_f32_e32 v138, v166, v138
	v_add_f32_e32 v138, v134, v138
	v_add_f32_e32 v138, v135, v138
	v_add_f32_e32 v138, v132, v138
	v_add_f32_e32 v220, v133, v138
	v_mov_b32_e32 v221, v220
	s_waitcnt lgkmcnt(0)
	v_mfma_f32_32x32x16_bf16 v[66:81], v[232:235], v[102:105], v[66:81]
	v_cvt_pk_bf16_f32 v138, v177, v226
	v_cvt_pk_bf16_f32 v139, v161, v223
	v_cvt_pk_bf16_f32 v140, v153, v176
	v_cvt_pk_bf16_f32 v141, v152, v160
	v_cvt_pk_bf16_f32 v222, v149, v151
	v_cvt_pk_bf16_f32 v223, v147, v150
	v_cvt_pk_bf16_f32 v224, v145, v148
	v_permlane32_swap_b32_e32 v220, v221
	v_permlane32_swap_b32_e32 v138, v140
	v_cvt_pk_bf16_f32 v225, v144, v146
	v_permlane32_swap_b32_e32 v222, v224
	v_cvt_pk_bf16_f32 v144, v143, v164
	v_cvt_pk_bf16_f32 v145, v136, v137
	v_cvt_pk_bf16_f32 v146, v130, v131
	v_cvt_pk_bf16_f32 v147, v128, v129
	v_cvt_pk_bf16_f32 v148, v126, v127
	v_cvt_pk_bf16_f32 v149, v165, v166
	v_cvt_pk_bf16_f32 v150, v134, v135
	v_cvt_pk_bf16_f32 v151, v132, v133
	v_permlane32_swap_b32_e32 v139, v141
	v_permlane32_swap_b32_e32 v223, v225
	v_permlane32_swap_b32_e32 v144, v146
	v_permlane32_swap_b32_e32 v145, v147
	v_permlane32_swap_b32_e32 v148, v150
	v_permlane32_swap_b32_e32 v149, v151
	global_load_dwordx4 v[182:185], v[178:179], off offset:2048
	global_load_dwordx4 v[194:197], v[180:181], off offset:2048
	global_load_dwordx4 v[134:137], v[204:205], off offset:1024
	s_mov_b32 s4, 0xa0000
	s_mov_b32 s5, 0
	s_nop 0
	v_lshl_add_u64 v[178:179], v[178:179], 0, s[4:5]
	v_lshl_add_u64 v[180:181], v[180:181], 0, s[4:5]
	v_lshl_add_u64 v[204:205], v[204:205], 0, s[4:5]
	ds_read_b64_tr_b16 v[226:227], v211 offset:0
	ds_read_b64_tr_b16 v[228:229], v211 offset:0x800
	ds_read_b64_tr_b16 v[230:231], v211 offset:0x1000
	ds_read_b64_tr_b16 v[232:233], v211 offset:0x1800
	ds_read_b64_tr_b16 v[234:235], v211 offset:0x2000
	ds_read_b64_tr_b16 v[236:237], v211 offset:0x2800
	ds_read_b64_tr_b16 v[238:239], v211 offset:0x3000
	ds_read_b64_tr_b16 v[240:241], v211 offset:0x3800
	s_waitcnt lgkmcnt(4)
	s_nop 0
	v_mfma_f32_32x32x16_bf16 v[18:33], v[138:141], v[226:229], v[18:33]
	ds_read_b64_tr_b16 v[226:227], v211 offset:0x200
	ds_read_b64_tr_b16 v[228:229], v211 offset:0xa00
	v_mfma_f32_32x32x16_bf16 v[18:33], v[222:225], v[230:233], v[18:33]
	ds_read_b64_tr_b16 v[230:231], v211 offset:0x1200
	ds_read_b64_tr_b16 v[232:233], v211 offset:0x1a00
	s_waitcnt lgkmcnt(4)
	v_mfma_f32_32x32x16_bf16 v[18:33], v[144:147], v[234:237], v[18:33]
	ds_read_b64_tr_b16 v[234:235], v211 offset:0x2200
	ds_read_b64_tr_b16 v[236:237], v211 offset:0x2a00
	v_mfma_f32_32x32x16_bf16 v[18:33], v[148:151], v[238:241], v[18:33]
	ds_read_b64_tr_b16 v[238:239], v211 offset:0x3200
	ds_read_b64_tr_b16 v[240:241], v211 offset:0x3a00
	s_waitcnt lgkmcnt(4)
	v_mfma_f32_32x32x16_bf16 v[2:17], v[138:141], v[226:229], v[2:17]
	ds_read_b64_tr_b16 v[226:227], v211 offset:0x400
	ds_read_b64_tr_b16 v[228:229], v211 offset:0xc00
	v_mfma_f32_32x32x16_bf16 v[2:17], v[222:225], v[230:233], v[2:17]
	ds_read_b64_tr_b16 v[230:231], v211 offset:0x1400
	ds_read_b64_tr_b16 v[232:233], v211 offset:0x1c00
	s_waitcnt lgkmcnt(4)
	v_mfma_f32_32x32x16_bf16 v[2:17], v[144:147], v[234:237], v[2:17]
	ds_read_b64_tr_b16 v[234:235], v211 offset:0x2400
	ds_read_b64_tr_b16 v[236:237], v211 offset:0x2c00
	v_mfma_f32_32x32x16_bf16 v[2:17], v[148:151], v[238:241], v[2:17]
	ds_read_b64_tr_b16 v[238:239], v211 offset:0x3400
	ds_read_b64_tr_b16 v[240:241], v211 offset:0x3c00
	s_waitcnt lgkmcnt(4)
; #define SBAR() __builtin_amdgcn_sched_barrier(0)
; __device__ __forceinline__ void partialSM(f32x16& p0, f32x16& p1, float& m_reg, float& mn, float& alpha, float C, float thrRaw) {
;   float pmax = p0[0];
; #pragma unroll
;   for (int r = 1; r < 16; ++r) pmax = fmaxf(pmax, p0[r]);
; #pragma unroll
;   for (int r = 0; r < 16; ++r) pmax = fmaxf(pmax, p1[r]);
;   { auto rr = __builtin_amdgcn_permlane32_swap(__float_as_uint(pmax), __float_as_uint(pmax), false, false);
;     pmax = fmaxf(__uint_as_float(rr[0]), __uint_as_float(rr[1])); }
;   if (__builtin_expect(__all(pmax - m_reg <= thrRaw), 1)) { mn = m_reg; alpha = 1.f; }
;   else { mn = fmaxf(m_reg, pmax); alpha = __builtin_amdgcn_exp2f((m_reg - mn) * C); m_reg = mn; }
;   float mnC = -mn * C;
; #pragma unroll
;   for (int r = 0; r < 16; ++r) p0[r] = fmaf(p0[r], C, mnC);
; #pragma unroll
;   for (int r = 0; r < 16; ++r) p1[r] = fmaf(p1[r], C, mnC);
; #pragma unroll
;   for (int r = 0; r < 16; ++r) p0[r] = __builtin_amdgcn_exp2f(p0[r]);
; }
; template <int D0> __device__ __forceinline__ void pv_one(f32x16& od, int vb, bf16x8 pa0, bf16x8 pa1, bf16x8 pa2, bf16x8 pa3) {
;   const s16x4 l0 = tr_read<v_rd_off(D0, 0, 0)>(vb), h0 = tr_read<v_rd_off(D0, 0, 1)>(vb), l1 = tr_read<v_rd_off(D0, 1, 0)>(vb), h1 = tr_read<v_rd_off(D0, 1, 1)>(vb);
;   const s16x4 l2 = tr_read<v_rd_off(D0, 2, 0)>(vb), h2 = tr_read<v_rd_off(D0, 2, 1)>(vb), l3 = tr_read<v_rd_off(D0, 3, 0)>(vb), h3 = tr_read<v_rd_off(D0, 3, 1)>(vb);
;   asm volatile("s_waitcnt lgkmcnt(0)" ::: "memory"); SBAR();
;     ...
;   od = __builtin_amdgcn_mfma_f32_32x32x16_bf16(pa0, PK(l0, h0), od, 0, 0, 0);
;   od = __builtin_amdgcn_mfma_f32_32x32x16_bf16(pa1, PK(l1, h1), od, 0, 0, 0);
;   od = __builtin_amdgcn_mfma_f32_32x32x16_bf16(pa2, PK(l2, h2), od, 0, 0, 0);
;   od = __builtin_amdgcn_mfma_f32_32x32x16_bf16(pa3, PK(l3, h3), od, 0, 0, 0);
;     ...
; }
; __device__ __forceinline__ void pv_d0(f32x16* o, int vb, bf16x8 pa0, bf16x8 pa1, bf16x8 pa2, bf16x8 pa3) {
;   pv_one<0>(o[0], vb, pa0, pa1, pa2, pa3); pv_one<1>(o[1], vb, pa0, pa1, pa2, pa3); pv_one<2>(o[2], vb, pa0, pa1, pa2, pa3); pv_one<3>(o[3], vb, pa0, pa1, pa2, pa3);
	v_mfma_f32_32x32x16_bf16 v[50:65], v[138:141], v[226:229], v[50:65]
	ds_read_b64_tr_b16 v[226:227], v211 offset:0x600
	ds_read_b64_tr_b16 v[228:229], v211 offset:0xe00
	v_mfma_f32_32x32x16_bf16 v[50:65], v[222:225], v[230:233], v[50:65]
	ds_read_b64_tr_b16 v[230:231], v211 offset:0x1600
	ds_read_b64_tr_b16 v[232:233], v211 offset:0x1e00
	s_waitcnt lgkmcnt(4)
	v_mfma_f32_32x32x16_bf16 v[50:65], v[144:147], v[234:237], v[50:65]
	ds_read_b64_tr_b16 v[234:235], v211 offset:0x2600
	ds_read_b64_tr_b16 v[236:237], v211 offset:0x2e00
	v_mfma_f32_32x32x16_bf16 v[50:65], v[148:151], v[238:241], v[50:65]
	ds_read_b64_tr_b16 v[238:239], v211 offset:0x3600
	ds_read_b64_tr_b16 v[240:241], v211 offset:0x3e00
	s_waitcnt lgkmcnt(6)
	v_mfma_f32_32x32x16_bf16 v[34:49], v[138:141], v[226:229], v[34:49]
	v_max_f32_e32 v138, v83, v82
	v_max3_f32 v138, v138, v84, v85
	v_max3_f32 v138, v138, v86, v87
	v_max3_f32 v138, v138, v88, v89
	v_max3_f32 v138, v138, v90, v91
	v_max3_f32 v138, v138, v92, v93
	v_max3_f32 v138, v138, v94, v95
	s_waitcnt lgkmcnt(4)
	v_mfma_f32_32x32x16_bf16 v[34:49], v[222:225], v[230:233], v[34:49]
	v_max3_f32 v138, v138, v96, v97
	v_max3_f32 v138, v138, v66, v67
	v_max3_f32 v138, v138, v68, v69
	v_max3_f32 v138, v138, v70, v71
	v_max3_f32 v138, v138, v72, v73
	v_max3_f32 v138, v138, v74, v75
	v_max3_f32 v138, v138, v76, v77
	v_max3_f32 v138, v138, v78, v79
	s_waitcnt lgkmcnt(2)
	v_mfma_f32_32x32x16_bf16 v[34:49], v[144:147], v[234:237], v[34:49]
	v_max3_f32 v138, v138, v80, v81
	v_mov_b32_e32 v139, v138
	s_nop 1
	v_permlane32_swap_b32_e32 v138, v139
	v_max_f32_e32 v138, v139, v138
	v_sub_f32_e32 v139, v138, v142
	s_mov_b32 s2, 0x42800000
	v_cmp_ge_f32_e32 vcc, s2, v139
	v_max_f32_e32 v138, v142, v138
	s_waitcnt lgkmcnt(0)
	v_mfma_f32_32x32x16_bf16 v[34:49], v[148:151], v[238:241], v[34:49]
	v_sub_f32_e32 v139, v142, v138
	v_mul_f32_e32 v139, 0x3e38aa3b, v139
	v_exp_f32_e32 v139, v139
	s_cmp_eq_u64 vcc, exec
	s_cselect_b64 s[2:3], -1, 0
	s_waitcnt vmcnt(3)
	v_cndmask_b32_e64 v222, v139, 1.0, s[2:3]
	v_cmp_gt_f32_e32 vcc, 1.0, v222
	ds_write_b128 v213, v[122:125] offset:32768
	s_cbranch_vccz .LBB0_686
	s_and_saveexec_b64 s[4:5], s[0:1]
	ds_write_b32 v208, v222 offset:128
	s_or_b64 exec, exec, s[4:5]
	s_waitcnt lgkmcnt(0)
	v_add_u32_e32 v139, v207, v0
	ds_read_b128 v[144:147], v139 offset:128
	ds_read_b128 v[148:151], v139 offset:160
	ds_read_b128 v[224:227], v139 offset:192
	ds_read_b128 v[228:231], v139 offset:224
	s_waitcnt lgkmcnt(3)
	v_pk_mul_f32 v[2:3], v[144:145], v[2:3]
	v_pk_mul_f32 v[4:5], v[4:5], v[146:147]
	s_waitcnt lgkmcnt(2)
	v_pk_mul_f32 v[6:7], v[6:7], v[148:149]
	v_pk_mul_f32 v[8:9], v[8:9], v[150:151]
	s_waitcnt lgkmcnt(1)
	v_pk_mul_f32 v[10:11], v[10:11], v[224:225]
	v_pk_mul_f32 v[12:13], v[12:13], v[226:227]
	s_waitcnt lgkmcnt(0)
	v_pk_mul_f32 v[14:15], v[14:15], v[228:229]
	v_pk_mul_f32 v[30:31], v[30:31], v[228:229]
	v_pk_mul_f32 v[26:27], v[26:27], v[224:225]
	v_pk_mul_f32 v[22:23], v[22:23], v[148:149]
	v_pk_mul_f32 v[32:33], v[32:33], v[230:231]
	v_pk_mul_f32 v[28:29], v[28:29], v[226:227]
	v_pk_mul_f32 v[24:25], v[24:25], v[150:151]
	v_pk_mul_f32 v[20:21], v[20:21], v[146:147]
	v_pk_mul_f32 v[18:19], v[18:19], v[144:145]
	v_pk_mul_f32 v[16:17], v[16:17], v[230:231]
	v_pk_mul_f32 v[34:35], v[144:145], v[34:35]
	v_pk_mul_f32 v[36:37], v[36:37], v[146:147]
	v_pk_mul_f32 v[38:39], v[38:39], v[148:149]
	v_pk_mul_f32 v[40:41], v[40:41], v[150:151]
	v_pk_mul_f32 v[42:43], v[42:43], v[224:225]
	v_pk_mul_f32 v[44:45], v[44:45], v[226:227]
	v_pk_mul_f32 v[46:47], v[46:47], v[228:229]
	v_pk_mul_f32 v[62:63], v[62:63], v[228:229]
	v_pk_mul_f32 v[58:59], v[58:59], v[224:225]
	v_pk_mul_f32 v[54:55], v[54:55], v[148:149]
	v_pk_mul_f32 v[64:65], v[64:65], v[230:231]
	v_pk_mul_f32 v[60:61], v[60:61], v[226:227]
	v_pk_mul_f32 v[56:57], v[56:57], v[150:151]
	v_pk_mul_f32 v[52:53], v[52:53], v[146:147]
	v_pk_mul_f32 v[50:51], v[50:51], v[144:145]
	v_pk_mul_f32 v[48:49], v[48:49], v[230:231]
.LBB0_686:
	v_cndmask_b32_e64 v223, v138, v142, s[2:3]
	v_mul_f32_e32 v224, 0xbe38aa3b, v223
	v_fmamk_f32 v82, v82, 0x3e38aa3b, v224
	v_fmamk_f32 v83, v83, 0x3e38aa3b, v224
	v_fmamk_f32 v84, v84, 0x3e38aa3b, v224
	v_fmamk_f32 v85, v85, 0x3e38aa3b, v224
	v_fmamk_f32 v86, v86, 0x3e38aa3b, v224
	v_fmamk_f32 v87, v87, 0x3e38aa3b, v224
	v_fmamk_f32 v88, v88, 0x3e38aa3b, v224
	v_fmamk_f32 v89, v89, 0x3e38aa3b, v224
	v_fmamk_f32 v90, v90, 0x3e38aa3b, v224
	v_fmamk_f32 v91, v91, 0x3e38aa3b, v224
	v_fmamk_f32 v92, v92, 0x3e38aa3b, v224
	v_fmamk_f32 v93, v93, 0x3e38aa3b, v224
	v_fmamk_f32 v94, v94, 0x3e38aa3b, v224
	v_fmamk_f32 v95, v95, 0x3e38aa3b, v224
	v_fmamk_f32 v96, v96, 0x3e38aa3b, v224
	v_fmamk_f32 v97, v97, 0x3e38aa3b, v224
	v_exp_f32_e32 v138, v82
	v_exp_f32_e32 v153, v83
	v_exp_f32_e32 v139, v84
	v_exp_f32_e32 v152, v85
	v_exp_f32_e32 v140, v86
	v_exp_f32_e32 v151, v87
	v_exp_f32_e32 v141, v88
	v_exp_f32_e32 v150, v89
	v_exp_f32_e32 v142, v90
	v_exp_f32_e32 v149, v91
	v_exp_f32_e32 v143, v92
	v_exp_f32_e32 v148, v93
	v_exp_f32_e32 v144, v94
	v_exp_f32_e32 v147, v95
	v_exp_f32_e32 v145, v96
	v_exp_f32_e32 v146, v97
	v_fmamk_f32 v233, v66, 0x3e38aa3b, v224
	v_fmamk_f32 v234, v67, 0x3e38aa3b, v224
	v_fmamk_f32 v235, v68, 0x3e38aa3b, v224
	v_fmamk_f32 v236, v69, 0x3e38aa3b, v224
	v_fmamk_f32 v237, v70, 0x3e38aa3b, v224
	v_fmamk_f32 v226, v71, 0x3e38aa3b, v224
	v_fmamk_f32 v227, v72, 0x3e38aa3b, v224
	v_fmamk_f32 v228, v73, 0x3e38aa3b, v224
	v_fmamk_f32 v229, v74, 0x3e38aa3b, v224
	v_fmamk_f32 v230, v75, 0x3e38aa3b, v224
	v_fmamk_f32 v231, v76, 0x3e38aa3b, v224
	v_fmamk_f32 v232, v77, 0x3e38aa3b, v224
	v_fmamk_f32 v225, v78, 0x3e38aa3b, v224
	v_fmamk_f32 v238, v79, 0x3e38aa3b, v224
	v_fmamk_f32 v239, v80, 0x3e38aa3b, v224
	v_fmac_f32_e32 v224, 0x3e38aa3b, v81
	s_waitcnt lgkmcnt(0)
	s_barrier
; #define SBAR() __builtin_amdgcn_sched_barrier(0)
; #define SLOAD(i, k0) do { sr_[i].vs0 = *reinterpret_cast<const bf16x8*>(&Vh[(long)((k0) + sr) * LDP + sc]); sr_[i].vs1 = *reinterpret_cast<const bf16x8*>(&Vh[(long)((k0) + 32 + sr) * LDP + sc]); \
;     sr_[i].ks0 = *reinterpret_cast<const bf16x8*>(&Kh[(long)((k0) + ksr) * LDP + ksc]); if (DK == 128) sr_[i].ks1 = *reinterpret_cast<const bf16x8*>(&Kh[(long)((k0) + 32 + ksr) * LDP + ksc]); } while (0)
; #define HOOK(P0, P1, j) do { if (NA) na_hook(P0, P1, krow0 + (j), q_row, q_col, win_r, win_c, rpb, inv_scale, hi); } while (0)
; __device__ __forceinline__ void finishSM(f32x16& p0, f32x16& p1, float alpha, float& l_reg, bf16x8& pa0, bf16x8& pa1, bf16x8& pa2, bf16x8& pa3) {
; #pragma unroll
;   for (int r = 0; r < 16; ++r) p1[r] = __builtin_amdgcn_exp2f(p1[r]);
;   float ps = 0;
; #pragma unroll
;   for (int r = 0; r < 16; ++r) ps += p0[r];
; #pragma unroll
;   for (int r = 0; r < 16; ++r) ps += p1[r];
;   { auto rr = __builtin_amdgcn_permlane32_swap(__float_as_uint(ps), __float_as_uint(ps), false, false);
;     ps = __uint_as_float(rr[0]) + __uint_as_float(rr[1]); }
;   l_reg = l_reg * alpha + ps;
;     ...
;   PK4(p0, 0, pa0); PK4(p0, 8, pa1); PK4(p1, 0, pa2); PK4(p1, 8, pa3);
;     ...
; }
; template <int DK, bool QL>
; __device__ __forceinline__ void qkt(f32x16& p0, f32x16& p1, const bf16* Ks, const bf16x8* qr, const char* ql, int r32, int hi) {
;   p0 = f32x16{}; p1 = f32x16{};
; #pragma unroll
;   for (int d0 = 0; d0 < DK / 16; ++d0) { int cb = (d0 * 16 + hi * 8) * 2;
;     const bf16x8 qv = QL ? *reinterpret_cast<const bf16x8*>(ql + d0 * 1024) : qr[d0];
;     bf16x8 b0 = *reinterpret_cast<const bf16x8*>((const char*)Ks + kswz<DK>(r32, cb));
;     bf16x8 b1 = *reinterpret_cast<const bf16x8*>((const char*)Ks + kswz<DK>(32 + r32, cb));
;     p0 = __builtin_amdgcn_mfma_f32_32x32x16_bf16(b0, qv, p0, 0, 0, 0);
;     p1 = __builtin_amdgcn_mfma_f32_32x32x16_bf16(b1, qv, p1, 0, 0, 0); }
; template <int DK, bool NA, bool QL, int SD> ...
;     ...
;     SBAR(); qkt<DK, QL>(pA0, pA1, K_lds, qr, ql, r32, hi); HOOK(pA0, pA1, j + 1);
;     finishSM(pB0, pB1, alB, l_reg, pa0, pa1, pa2, pa3); SBAR();
;     if (SD == 1 || j + 3 < NT) SLOAD(SE, (j + 1 + SD) * KVBLK); SBAR();
	ds_write_b128 v214, v[114:117]
	ds_write_b128 v215, v[118:121]
	ds_read_b128 v[66:69], v212 offset:32768
	ds_read_b128 v[70:73], v212 offset:36864
	v_exp_f32_e32 v164, v233
	v_exp_f32_e32 v233, v224
	v_add_f32_e32 v224, v153, v138
	s_waitcnt lgkmcnt(1)
	v_mfma_f32_32x32x16_bf16 v[82:97], v[66:69], v[110:113], 0
	v_add_f32_e32 v224, v139, v224
	v_add_f32_e32 v224, v152, v224
	v_add_f32_e32 v224, v140, v224
	ds_read_b128 v[240:243], v216 offset:32768
	ds_read_b128 v[244:247], v216 offset:36864
	v_add_f32_e32 v224, v151, v224
	v_add_f32_e32 v224, v141, v224
	v_add_f32_e32 v224, v150, v224
	s_waitcnt lgkmcnt(2)
	v_mfma_f32_32x32x16_bf16 v[66:81], v[70:73], v[110:113], 0
	v_add_f32_e32 v224, v142, v224
	v_add_f32_e32 v224, v149, v224
	v_add_f32_e32 v224, v143, v224
	v_add_f32_e32 v224, v148, v224
	v_add_f32_e32 v224, v144, v224
	v_exp_f32_e32 v165, v234
	v_add_f32_e32 v224, v147, v224
	s_waitcnt lgkmcnt(1)
	v_mfma_f32_32x32x16_bf16 v[82:97], v[240:243], v[106:109], v[82:97]
	v_exp_f32_e32 v166, v235
	v_add_f32_e32 v224, v145, v224
	v_exp_f32_e32 v167, v236
	v_add_f32_e32 v224, v146, v224
	v_exp_f32_e32 v172, v237
	v_add_f32_e32 v224, v164, v224
	v_exp_f32_e32 v173, v226
	s_waitcnt lgkmcnt(0)
	v_mfma_f32_32x32x16_bf16 v[66:81], v[244:247], v[106:109], v[66:81]
	ds_read_b128 v[240:243], v217 offset:32768
	ds_read_b128 v[244:247], v217 offset:36864
	v_add_f32_e32 v224, v165, v224
	v_exp_f32_e32 v174, v227
	v_add_f32_e32 v224, v166, v224
	v_exp_f32_e32 v175, v228
	v_add_f32_e32 v224, v167, v224
	v_exp_f32_e32 v226, v229
	s_waitcnt lgkmcnt(1)
	v_mfma_f32_32x32x16_bf16 v[82:97], v[240:243], v[98:101], v[82:97]
	v_add_f32_e32 v224, v172, v224
	v_exp_f32_e32 v227, v230
	v_add_f32_e32 v224, v173, v224
	v_exp_f32_e32 v228, v231
	v_add_f32_e32 v224, v174, v224
	v_exp_f32_e32 v229, v232
	v_add_f32_e32 v224, v175, v224
	s_waitcnt lgkmcnt(0)
	v_mfma_f32_32x32x16_bf16 v[66:81], v[244:247], v[98:101], v[66:81]
	ds_read_b128 v[240:243], v218 offset:32768
	ds_read_b128 v[244:247], v218 offset:36864
	v_exp_f32_e32 v230, v225
	v_add_f32_e32 v224, v226, v224
	v_exp_f32_e32 v231, v238
	v_add_f32_e32 v224, v227, v224
	v_exp_f32_e32 v232, v239
	v_add_f32_e32 v224, v228, v224
	s_waitcnt lgkmcnt(1)
	v_mfma_f32_32x32x16_bf16 v[82:97], v[240:243], v[102:105], v[82:97]
	v_add_f32_e32 v224, v229, v224
	v_add_f32_e32 v224, v230, v224
	v_add_f32_e32 v224, v231, v224
	v_add_f32_e32 v224, v232, v224
	v_add_f32_e32 v224, v233, v224
	v_mov_b32_e32 v225, v224
	v_cvt_pk_bf16_f32 v138, v138, v153
	s_waitcnt lgkmcnt(0)
	v_mfma_f32_32x32x16_bf16 v[66:81], v[244:247], v[102:105], v[66:81]
	v_cvt_pk_bf16_f32 v139, v139, v152
	v_cvt_pk_bf16_f32 v140, v140, v151
	v_cvt_pk_bf16_f32 v141, v141, v150
	v_cvt_pk_bf16_f32 v142, v142, v149
	v_cvt_pk_bf16_f32 v143, v143, v148
	v_cvt_pk_bf16_f32 v144, v144, v147
	v_cvt_pk_bf16_f32 v145, v145, v146
	v_cvt_pk_bf16_f32 v146, v164, v165
	v_cvt_pk_bf16_f32 v147, v166, v167
	v_cvt_pk_bf16_f32 v148, v172, v173
	v_cvt_pk_bf16_f32 v149, v174, v175
	v_cvt_pk_bf16_f32 v150, v226, v227
	v_cvt_pk_bf16_f32 v151, v228, v229
	v_cvt_pk_bf16_f32 v152, v230, v231
	v_cvt_pk_bf16_f32 v153, v232, v233
	v_permlane32_swap_b32_e32 v224, v225
	v_permlane32_swap_b32_e32 v138, v140
	v_permlane32_swap_b32_e32 v139, v141
	v_permlane32_swap_b32_e32 v142, v144
	v_permlane32_swap_b32_e32 v143, v145
	v_permlane32_swap_b32_e32 v146, v148
	v_permlane32_swap_b32_e32 v147, v149
	v_permlane32_swap_b32_e32 v150, v152
	v_permlane32_swap_b32_e32 v151, v153
	s_cmp_gt_u32 s9, 60
	s_cselect_b64 s[4:5], -1, 0
	s_and_b64 vcc, exec, s[4:5]
	s_cbranch_vccnz .Lod_d1
	global_load_dwordx4 v[114:117], v[178:179], off offset:2048
	global_load_dwordx4 v[118:121], v[180:181], off offset:2048
	global_load_dwordx4 v[122:125], v[204:205], off offset:1024
	s_mov_b32 s6, 0xa0000
	s_mov_b32 s7, 0
	s_nop 0
	v_lshl_add_u64 v[178:179], v[178:179], 0, s[6:7]
	v_lshl_add_u64 v[180:181], v[180:181], 0, s[6:7]
	v_lshl_add_u64 v[204:205], v[204:205], 0, s[6:7]
; #define SBAR() __builtin_amdgcn_sched_barrier(0)
; #define SWAIT() do { if (SD == 1) asm volatile("s_waitcnt vmcnt(0)" ::: "memory"); else if (DK == 128) asm volatile("s_waitcnt vmcnt(4)" ::: "memory"); else asm volatile("s_waitcnt vmcnt(3)" ::: "memory"); } while (0)
; #define RESC(a) do { if (__any((a) < 1.f)) { if (hi == 0) al_l[r32] = (a); asm volatile("s_waitcnt lgkmcnt(0)" ::: "memory"); \
;     _Pragma("unroll") for (int d = 0; d < 4; ++d) _Pragma("unroll") for (int r = 0; r < 16; ++r) o[d][r] *= al_l[crow(r, hi)]; } } while (0)
; template <int D0> __device__ __forceinline__ void pv_one(f32x16& od, int vb, bf16x8 pa0, bf16x8 pa1, bf16x8 pa2, bf16x8 pa3) {
;   const s16x4 l0 = tr_read<v_rd_off(D0, 0, 0)>(vb), h0 = tr_read<v_rd_off(D0, 0, 1)>(vb), l1 = tr_read<v_rd_off(D0, 1, 0)>(vb), h1 = tr_read<v_rd_off(D0, 1, 1)>(vb);
;   const s16x4 l2 = tr_read<v_rd_off(D0, 2, 0)>(vb), h2 = tr_read<v_rd_off(D0, 2, 1)>(vb), l3 = tr_read<v_rd_off(D0, 3, 0)>(vb), h3 = tr_read<v_rd_off(D0, 3, 1)>(vb);
;   asm volatile("s_waitcnt lgkmcnt(0)" ::: "memory"); SBAR();
;     ...
;   od = __builtin_amdgcn_mfma_f32_32x32x16_bf16(pa0, PK(l0, h0), od, 0, 0, 0);
;   od = __builtin_amdgcn_mfma_f32_32x32x16_bf16(pa1, PK(l1, h1), od, 0, 0, 0);
;   od = __builtin_amdgcn_mfma_f32_32x32x16_bf16(pa2, PK(l2, h2), od, 0, 0, 0);
;   od = __builtin_amdgcn_mfma_f32_32x32x16_bf16(pa3, PK(l3, h3), od, 0, 0, 0);
;     ...
; }
; __device__ __forceinline__ void pv_d0(f32x16* o, int vb, bf16x8 pa0, bf16x8 pa1, bf16x8 pa2, bf16x8 pa3) {
;   pv_one<0>(o[0], vb, pa0, pa1, pa2, pa3); pv_one<1>(o[1], vb, pa0, pa1, pa2, pa3); pv_one<2>(o[2], vb, pa0, pa1, pa2, pa3); pv_one<3>(o[3], vb, pa0, pa1, pa2, pa3);
; template <int DK, bool NA, bool QL, int SD> ...
;     ...
;     pv_d0(o, vb0 + (int)SHM_V, pa0, pa1, pa2, pa3); partialSM(pA0, pA1, m_reg, mnA, alA, C, thrRaw);
;     __syncthreads(); SWAIT(); SWRITE(1, SO);
;     RESC(alA); __syncthreads();
.LBB0_688:
	ds_read_b64_tr_b16 v[226:227], v210 offset:0
	ds_read_b64_tr_b16 v[228:229], v210 offset:0x800
	ds_read_b64_tr_b16 v[230:231], v210 offset:0x1000
	ds_read_b64_tr_b16 v[232:233], v210 offset:0x1800
	ds_read_b64_tr_b16 v[234:235], v210 offset:0x2000
	ds_read_b64_tr_b16 v[236:237], v210 offset:0x2800
	ds_read_b64_tr_b16 v[238:239], v210 offset:0x3000
	ds_read_b64_tr_b16 v[240:241], v210 offset:0x3800
	s_waitcnt lgkmcnt(4)
	s_nop 0
	v_mfma_f32_32x32x16_bf16 v[18:33], v[138:141], v[226:229], v[18:33]
	ds_read_b64_tr_b16 v[226:227], v210 offset:0x200
	ds_read_b64_tr_b16 v[228:229], v210 offset:0xa00
	v_mfma_f32_32x32x16_bf16 v[18:33], v[142:145], v[230:233], v[18:33]
	ds_read_b64_tr_b16 v[230:231], v210 offset:0x1200
	ds_read_b64_tr_b16 v[232:233], v210 offset:0x1a00
	s_waitcnt lgkmcnt(4)
	v_mfma_f32_32x32x16_bf16 v[18:33], v[146:149], v[234:237], v[18:33]
	ds_read_b64_tr_b16 v[234:235], v210 offset:0x2200
	ds_read_b64_tr_b16 v[236:237], v210 offset:0x2a00
	v_mfma_f32_32x32x16_bf16 v[18:33], v[150:153], v[238:241], v[18:33]
	ds_read_b64_tr_b16 v[238:239], v210 offset:0x3200
	ds_read_b64_tr_b16 v[240:241], v210 offset:0x3a00
	s_waitcnt lgkmcnt(4)
	v_mfma_f32_32x32x16_bf16 v[2:17], v[138:141], v[226:229], v[2:17]
	ds_read_b64_tr_b16 v[226:227], v210 offset:0x400
	ds_read_b64_tr_b16 v[228:229], v210 offset:0xc00
	v_mfma_f32_32x32x16_bf16 v[2:17], v[142:145], v[230:233], v[2:17]
	ds_read_b64_tr_b16 v[230:231], v210 offset:0x1400
	ds_read_b64_tr_b16 v[232:233], v210 offset:0x1c00
	s_waitcnt lgkmcnt(4)
	v_mfma_f32_32x32x16_bf16 v[2:17], v[146:149], v[234:237], v[2:17]
	ds_read_b64_tr_b16 v[234:235], v210 offset:0x2400
	ds_read_b64_tr_b16 v[236:237], v210 offset:0x2c00
	v_mfma_f32_32x32x16_bf16 v[2:17], v[150:153], v[238:241], v[2:17]
	ds_read_b64_tr_b16 v[238:239], v210 offset:0x3400
	ds_read_b64_tr_b16 v[240:241], v210 offset:0x3c00
	s_waitcnt lgkmcnt(4)
	v_mfma_f32_32x32x16_bf16 v[50:65], v[138:141], v[226:229], v[50:65]
	ds_read_b64_tr_b16 v[226:227], v210 offset:0x600
	ds_read_b64_tr_b16 v[228:229], v210 offset:0xe00
	v_mfma_f32_32x32x16_bf16 v[50:65], v[142:145], v[230:233], v[50:65]
	ds_read_b64_tr_b16 v[230:231], v210 offset:0x1600
	ds_read_b64_tr_b16 v[232:233], v210 offset:0x1e00
	s_waitcnt lgkmcnt(4)
	v_mfma_f32_32x32x16_bf16 v[50:65], v[146:149], v[234:237], v[50:65]
	ds_read_b64_tr_b16 v[234:235], v210 offset:0x2600
	ds_read_b64_tr_b16 v[236:237], v210 offset:0x2e00
	v_mfma_f32_32x32x16_bf16 v[50:65], v[150:153], v[238:241], v[50:65]
	ds_read_b64_tr_b16 v[238:239], v210 offset:0x3600
	ds_read_b64_tr_b16 v[240:241], v210 offset:0x3e00
	s_waitcnt lgkmcnt(6)
	v_mfma_f32_32x32x16_bf16 v[34:49], v[138:141], v[226:229], v[34:49]
	v_max_f32_e32 v138, v83, v82
	v_max3_f32 v138, v138, v84, v85
	v_max3_f32 v138, v138, v86, v87
	v_max3_f32 v138, v138, v88, v89
	v_max3_f32 v138, v138, v90, v91
	v_max3_f32 v138, v138, v92, v93
	v_max3_f32 v138, v138, v94, v95
	s_waitcnt lgkmcnt(4)
	v_mfma_f32_32x32x16_bf16 v[34:49], v[142:145], v[230:233], v[34:49]
	v_max3_f32 v138, v138, v96, v97
	v_max3_f32 v138, v138, v66, v67
	v_max3_f32 v138, v138, v68, v69
	v_max3_f32 v138, v138, v70, v71
	v_max3_f32 v138, v138, v72, v73
	v_max3_f32 v138, v138, v74, v75
	v_max3_f32 v138, v138, v76, v77
	v_max3_f32 v138, v138, v78, v79
	s_waitcnt lgkmcnt(2)
	v_mfma_f32_32x32x16_bf16 v[34:49], v[146:149], v[234:237], v[34:49]
	v_max3_f32 v138, v138, v80, v81
	v_mov_b32_e32 v139, v138
	s_nop 1
	v_permlane32_swap_b32_e32 v138, v139
	v_max_f32_e32 v138, v139, v138
	v_sub_f32_e32 v139, v138, v223
	s_mov_b32 s2, 0x42800000
	v_cmp_ge_f32_e32 vcc, s2, v139
	v_max_f32_e32 v138, v223, v138
	s_waitcnt lgkmcnt(0)
	v_mfma_f32_32x32x16_bf16 v[34:49], v[150:153], v[238:241], v[34:49]
	v_sub_f32_e32 v139, v223, v138
	v_mul_f32_e32 v139, 0x3e38aa3b, v139
	v_exp_f32_e32 v139, v139
	s_cmp_eq_u64 vcc, exec
	s_cselect_b64 s[2:3], -1, 0
	s_waitcnt vmcnt(3)
	v_cndmask_b32_e64 v143, v139, 1.0, s[2:3]
	v_cmp_gt_f32_e32 vcc, 1.0, v143
	ds_write_b128 v213, v[134:137] offset:49152
	s_cbranch_vccz .LBB0_692
	s_and_saveexec_b64 s[6:7], s[0:1]
	ds_write_b32 v208, v143 offset:128
	s_or_b64 exec, exec, s[6:7]
	s_waitcnt lgkmcnt(0)
	v_add_u32_e32 v139, v207, v0
	ds_read_b128 v[126:129], v139 offset:128
	ds_read_b128 v[130:133], v139 offset:160
	ds_read_b128 v[134:137], v139 offset:224
	ds_read_b128 v[144:147], v139 offset:192
	s_waitcnt lgkmcnt(3)
	v_pk_mul_f32 v[50:51], v[126:127], v[50:51]
	v_pk_mul_f32 v[52:53], v[128:129], v[52:53]
	s_waitcnt lgkmcnt(2)
	v_pk_mul_f32 v[54:55], v[130:131], v[54:55]
	s_waitcnt lgkmcnt(1)
	v_pk_mul_f32 v[30:31], v[30:31], v[134:135]
	s_waitcnt lgkmcnt(0)
	v_pk_mul_f32 v[26:27], v[26:27], v[144:145]
	v_pk_mul_f32 v[22:23], v[22:23], v[130:131]
	v_pk_mul_f32 v[32:33], v[32:33], v[136:137]
	v_pk_mul_f32 v[28:29], v[28:29], v[146:147]
	v_pk_mul_f32 v[24:25], v[24:25], v[132:133]
	v_pk_mul_f32 v[20:21], v[20:21], v[128:129]
	v_pk_mul_f32 v[18:19], v[18:19], v[126:127]
	v_pk_mul_f32 v[14:15], v[134:135], v[14:15]
	v_pk_mul_f32 v[10:11], v[144:145], v[10:11]
	v_pk_mul_f32 v[6:7], v[130:131], v[6:7]
	v_pk_mul_f32 v[16:17], v[136:137], v[16:17]
	v_pk_mul_f32 v[12:13], v[146:147], v[12:13]
	v_pk_mul_f32 v[8:9], v[132:133], v[8:9]
	v_pk_mul_f32 v[4:5], v[128:129], v[4:5]
	v_pk_mul_f32 v[2:3], v[126:127], v[2:3]
	v_pk_mul_f32 v[56:57], v[132:133], v[56:57]
	v_pk_mul_f32 v[34:35], v[126:127], v[34:35]
	v_pk_mul_f32 v[36:37], v[36:37], v[128:129]
	v_pk_mul_f32 v[38:39], v[38:39], v[130:131]
	v_pk_mul_f32 v[40:41], v[40:41], v[132:133]
	v_pk_mul_f32 v[58:59], v[58:59], v[144:145]
	v_pk_mul_f32 v[42:43], v[42:43], v[144:145]
	v_pk_mul_f32 v[60:61], v[60:61], v[146:147]
	v_pk_mul_f32 v[44:45], v[44:45], v[146:147]
	v_pk_mul_f32 v[62:63], v[62:63], v[134:135]
	v_pk_mul_f32 v[46:47], v[46:47], v[134:135]
	v_pk_mul_f32 v[64:65], v[64:65], v[136:137]
	v_pk_mul_f32 v[48:49], v[48:49], v[136:137]

; #define SBAR() __builtin_amdgcn_sched_barrier(0)
; __device__ __forceinline__ void finishSM(f32x16& p0, f32x16& p1, float alpha, float& l_reg, bf16x8& pa0, bf16x8& pa1, bf16x8& pa2, bf16x8& pa3) {
; #pragma unroll
;   for (int r = 0; r < 16; ++r) p1[r] = __builtin_amdgcn_exp2f(p1[r]);
;   float ps = 0;
; #pragma unroll
;   for (int r = 0; r < 16; ++r) ps += p0[r];
; #pragma unroll
;   for (int r = 0; r < 16; ++r) ps += p1[r];
;   { auto rr = __builtin_amdgcn_permlane32_swap(__float_as_uint(ps), __float_as_uint(ps), false, false);
;     ps = __uint_as_float(rr[0]) + __uint_as_float(rr[1]); }
;   l_reg = l_reg * alpha + ps;
;     ...
;   PK4(p0, 0, pa0); PK4(p0, 8, pa1); PK4(p1, 0, pa2); PK4(p1, 8, pa3);
;     ...
; }
; template <int DK, bool QL>
; __device__ __forceinline__ void qkt(f32x16& p0, f32x16& p1, const bf16* Ks, const bf16x8* qr, const char* ql, int r32, int hi) {
;   p0 = f32x16{}; p1 = f32x16{};
; #pragma unroll
;   for (int d0 = 0; d0 < DK / 16; ++d0) { int cb = (d0 * 16 + hi * 8) * 2;
;     const bf16x8 qv = QL ? *reinterpret_cast<const bf16x8*>(ql + d0 * 1024) : qr[d0];
;     bf16x8 b0 = *reinterpret_cast<const bf16x8*>((const char*)Ks + kswz<DK>(r32, cb));
;     bf16x8 b1 = *reinterpret_cast<const bf16x8*>((const char*)Ks + kswz<DK>(32 + r32, cb));
;     p0 = __builtin_amdgcn_mfma_f32_32x32x16_bf16(b0, qv, p0, 0, 0, 0);
;     p1 = __builtin_amdgcn_mfma_f32_32x32x16_bf16(b1, qv, p1, 0, 0, 0); }
; template <int D0> __device__ __forceinline__ void pv_one(f32x16& od, int vb, bf16x8 pa0, bf16x8 pa1, bf16x8 pa2, bf16x8 pa3) {
;   const s16x4 l0 = tr_read<v_rd_off(D0, 0, 0)>(vb), h0 = tr_read<v_rd_off(D0, 0, 1)>(vb), l1 = tr_read<v_rd_off(D0, 1, 0)>(vb), h1 = tr_read<v_rd_off(D0, 1, 1)>(vb);
;   const s16x4 l2 = tr_read<v_rd_off(D0, 2, 0)>(vb), h2 = tr_read<v_rd_off(D0, 2, 1)>(vb), l3 = tr_read<v_rd_off(D0, 3, 0)>(vb), h3 = tr_read<v_rd_off(D0, 3, 1)>(vb);
;   asm volatile("s_waitcnt lgkmcnt(0)" ::: "memory"); SBAR();
;     ...
;   od = __builtin_amdgcn_mfma_f32_32x32x16_bf16(pa0, PK(l0, h0), od, 0, 0, 0);
;   od = __builtin_amdgcn_mfma_f32_32x32x16_bf16(pa1, PK(l1, h1), od, 0, 0, 0);
;   od = __builtin_amdgcn_mfma_f32_32x32x16_bf16(pa2, PK(l2, h2), od, 0, 0, 0);
;   od = __builtin_amdgcn_mfma_f32_32x32x16_bf16(pa3, PK(l3, h3), od, 0, 0, 0);
;     ...
; }
; __device__ __forceinline__ void pv_d0(f32x16* o, int vb, bf16x8 pa0, bf16x8 pa1, bf16x8 pa2, bf16x8 pa3) {
.LBB0_701:
	ds_read_b128 v[66:69], v215 offset:49152
	ds_read_b128 v[70:73], v215 offset:53248
	v_exp_f32_e32 v143, v138
	v_add_f32_e32 v138, v226, v177
	s_waitcnt lgkmcnt(1)
	v_mfma_f32_32x32x16_bf16 v[82:97], v[66:69], v[110:113], 0
	v_add_f32_e32 v138, v161, v138
	v_add_f32_e32 v138, v223, v138
	v_add_f32_e32 v138, v153, v138
	ds_read_b128 v[228:231], v216 offset:49152
	ds_read_b128 v[232:235], v216 offset:53248
	v_add_f32_e32 v138, v176, v138
	v_add_f32_e32 v138, v152, v138
	v_add_f32_e32 v138, v160, v138
	s_waitcnt lgkmcnt(2)
	v_mfma_f32_32x32x16_bf16 v[66:81], v[70:73], v[110:113], 0
	v_add_f32_e32 v138, v149, v138
	v_add_f32_e32 v138, v151, v138
	v_add_f32_e32 v138, v147, v138
	v_add_f32_e32 v138, v150, v138
	v_add_f32_e32 v138, v145, v138
	v_exp_f32_e32 v164, v139
	v_add_f32_e32 v138, v148, v138
	s_waitcnt lgkmcnt(1)
	v_mfma_f32_32x32x16_bf16 v[82:97], v[228:231], v[106:109], v[82:97]
	v_exp_f32_e32 v136, v136
	v_add_f32_e32 v138, v144, v138
	v_exp_f32_e32 v137, v137
	v_add_f32_e32 v138, v146, v138
	v_exp_f32_e32 v130, v130
	v_add_f32_e32 v138, v143, v138
	v_exp_f32_e32 v131, v131
	s_waitcnt lgkmcnt(0)
	v_mfma_f32_32x32x16_bf16 v[66:81], v[232:235], v[106:109], v[66:81]
	ds_read_b128 v[228:231], v217 offset:49152
	ds_read_b128 v[232:235], v217 offset:53248
	v_add_f32_e32 v138, v164, v138
	v_exp_f32_e32 v128, v128
	v_add_f32_e32 v138, v136, v138
	v_exp_f32_e32 v129, v129
	v_add_f32_e32 v138, v137, v138
	v_exp_f32_e32 v126, v126
	s_waitcnt lgkmcnt(1)
	v_mfma_f32_32x32x16_bf16 v[82:97], v[228:231], v[102:105], v[82:97]
	v_add_f32_e32 v138, v130, v138
	v_exp_f32_e32 v127, v127
	v_add_f32_e32 v138, v131, v138
	v_exp_f32_e32 v165, v140
	v_add_f32_e32 v138, v128, v138
	v_exp_f32_e32 v166, v141
	v_add_f32_e32 v138, v129, v138
	s_waitcnt lgkmcnt(0)
	v_mfma_f32_32x32x16_bf16 v[66:81], v[232:235], v[102:105], v[66:81]
	ds_read_b128 v[228:231], v218 offset:49152
	ds_read_b128 v[232:235], v218 offset:53248
	v_exp_f32_e32 v134, v134
	v_add_f32_e32 v138, v126, v138
	v_exp_f32_e32 v135, v135
	v_add_f32_e32 v138, v127, v138
	v_exp_f32_e32 v132, v132
	v_add_f32_e32 v138, v165, v138
	s_waitcnt lgkmcnt(1)
	v_mfma_f32_32x32x16_bf16 v[82:97], v[228:231], v[98:101], v[82:97]
	v_exp_f32_e32 v133, v133
	v_add_f32_e32 v138, v166, v138
	v_add_f32_e32 v138, v134, v138
	v_add_f32_e32 v138, v135, v138
	v_add_f32_e32 v138, v132, v138
	v_add_f32_e32 v220, v133, v138
	v_mov_b32_e32 v221, v220
	s_waitcnt lgkmcnt(0)
	v_mfma_f32_32x32x16_bf16 v[66:81], v[232:235], v[98:101], v[66:81]
	v_cvt_pk_bf16_f32 v138, v177, v226
	v_cvt_pk_bf16_f32 v139, v161, v223
	v_cvt_pk_bf16_f32 v140, v153, v176
	v_cvt_pk_bf16_f32 v141, v152, v160
	v_cvt_pk_bf16_f32 v222, v149, v151
	v_cvt_pk_bf16_f32 v223, v147, v150
	v_cvt_pk_bf16_f32 v224, v145, v148
	v_permlane32_swap_b32_e32 v220, v221
	v_permlane32_swap_b32_e32 v138, v140
	v_cvt_pk_bf16_f32 v225, v144, v146
	v_permlane32_swap_b32_e32 v222, v224
	v_cvt_pk_bf16_f32 v144, v143, v164
	v_cvt_pk_bf16_f32 v145, v136, v137
	v_cvt_pk_bf16_f32 v146, v130, v131
	v_cvt_pk_bf16_f32 v147, v128, v129
	v_cvt_pk_bf16_f32 v148, v126, v127
	v_cvt_pk_bf16_f32 v149, v165, v166
	v_cvt_pk_bf16_f32 v150, v134, v135
	v_cvt_pk_bf16_f32 v151, v132, v133
	v_permlane32_swap_b32_e32 v139, v141
	v_permlane32_swap_b32_e32 v223, v225
	v_permlane32_swap_b32_e32 v144, v146
	v_permlane32_swap_b32_e32 v145, v147
	v_permlane32_swap_b32_e32 v148, v150
	v_permlane32_swap_b32_e32 v149, v151
	global_load_dwordx4 v[182:185], v[178:179], off offset:2048
	global_load_dwordx4 v[194:197], v[180:181], off offset:2048
	global_load_dwordx4 v[134:137], v[204:205], off offset:1152
	s_mov_b32 s4, 0xa0000
	s_mov_b32 s5, 0
	s_nop 0
	v_lshl_add_u64 v[178:179], v[178:179], 0, s[4:5]
	v_lshl_add_u64 v[180:181], v[180:181], 0, s[4:5]
	v_lshl_add_u64 v[204:205], v[204:205], 0, s[4:5]
	ds_read_b64_tr_b16 v[226:227], v211 offset:0
	ds_read_b64_tr_b16 v[228:229], v211 offset:0x800
	ds_read_b64_tr_b16 v[230:231], v211 offset:0x1000
	ds_read_b64_tr_b16 v[232:233], v211 offset:0x1800
	ds_read_b64_tr_b16 v[234:235], v211 offset:0x2000
	ds_read_b64_tr_b16 v[236:237], v211 offset:0x2800
	ds_read_b64_tr_b16 v[238:239], v211 offset:0x3000
	ds_read_b64_tr_b16 v[240:241], v211 offset:0x3800
	s_waitcnt lgkmcnt(4)
	s_nop 0
	v_mfma_f32_32x32x16_bf16 v[2:17], v[138:141], v[226:229], v[2:17]
	ds_read_b64_tr_b16 v[226:227], v211 offset:0x200
	ds_read_b64_tr_b16 v[228:229], v211 offset:0xa00
	v_mfma_f32_32x32x16_bf16 v[2:17], v[222:225], v[230:233], v[2:17]
	ds_read_b64_tr_b16 v[230:231], v211 offset:0x1200
	ds_read_b64_tr_b16 v[232:233], v211 offset:0x1a00
	s_waitcnt lgkmcnt(4)
	v_mfma_f32_32x32x16_bf16 v[2:17], v[144:147], v[234:237], v[2:17]
	ds_read_b64_tr_b16 v[234:235], v211 offset:0x2200
	ds_read_b64_tr_b16 v[236:237], v211 offset:0x2a00
	v_mfma_f32_32x32x16_bf16 v[2:17], v[148:151], v[238:241], v[2:17]
	ds_read_b64_tr_b16 v[238:239], v211 offset:0x3200
	ds_read_b64_tr_b16 v[240:241], v211 offset:0x3a00
	s_waitcnt lgkmcnt(4)
	v_mfma_f32_32x32x16_bf16 v[50:65], v[138:141], v[226:229], v[50:65]
	ds_read_b64_tr_b16 v[226:227], v211 offset:0x400
	ds_read_b64_tr_b16 v[228:229], v211 offset:0xc00
	v_mfma_f32_32x32x16_bf16 v[50:65], v[222:225], v[230:233], v[50:65]
	ds_read_b64_tr_b16 v[230:231], v211 offset:0x1400
	ds_read_b64_tr_b16 v[232:233], v211 offset:0x1c00
	s_waitcnt lgkmcnt(4)
	v_mfma_f32_32x32x16_bf16 v[50:65], v[144:147], v[234:237], v[50:65]
	ds_read_b64_tr_b16 v[234:235], v211 offset:0x2400
	ds_read_b64_tr_b16 v[236:237], v211 offset:0x2c00
	v_mfma_f32_32x32x16_bf16 v[50:65], v[148:151], v[238:241], v[50:65]
	ds_read_b64_tr_b16 v[238:239], v211 offset:0x3400
	ds_read_b64_tr_b16 v[240:241], v211 offset:0x3c00
	s_waitcnt lgkmcnt(4)
; #define SBAR() __builtin_amdgcn_sched_barrier(0)
; __device__ __forceinline__ void partialSM(f32x16& p0, f32x16& p1, float& m_reg, float& mn, float& alpha, float C, float thrRaw) {
;   float pmax = p0[0];
; #pragma unroll
;   for (int r = 1; r < 16; ++r) pmax = fmaxf(pmax, p0[r]);
; #pragma unroll
;   for (int r = 0; r < 16; ++r) pmax = fmaxf(pmax, p1[r]);
;   { auto rr = __builtin_amdgcn_permlane32_swap(__float_as_uint(pmax), __float_as_uint(pmax), false, false);
;     pmax = fmaxf(__uint_as_float(rr[0]), __uint_as_float(rr[1])); }
;   if (__builtin_expect(__all(pmax - m_reg <= thrRaw), 1)) { mn = m_reg; alpha = 1.f; }
;   else { mn = fmaxf(m_reg, pmax); alpha = __builtin_amdgcn_exp2f((m_reg - mn) * C); m_reg = mn; }
;   float mnC = -mn * C;
; #pragma unroll
;   for (int r = 0; r < 16; ++r) p0[r] = fmaf(p0[r], C, mnC);
; #pragma unroll
;   for (int r = 0; r < 16; ++r) p1[r] = fmaf(p1[r], C, mnC);
; #pragma unroll
;   for (int r = 0; r < 16; ++r) p0[r] = __builtin_amdgcn_exp2f(p0[r]);
; }
; template <int D0> __device__ __forceinline__ void pv_one(f32x16& od, int vb, bf16x8 pa0, bf16x8 pa1, bf16x8 pa2, bf16x8 pa3) {
;   const s16x4 l0 = tr_read<v_rd_off(D0, 0, 0)>(vb), h0 = tr_read<v_rd_off(D0, 0, 1)>(vb), l1 = tr_read<v_rd_off(D0, 1, 0)>(vb), h1 = tr_read<v_rd_off(D0, 1, 1)>(vb);
;   const s16x4 l2 = tr_read<v_rd_off(D0, 2, 0)>(vb), h2 = tr_read<v_rd_off(D0, 2, 1)>(vb), l3 = tr_read<v_rd_off(D0, 3, 0)>(vb), h3 = tr_read<v_rd_off(D0, 3, 1)>(vb);
;   asm volatile("s_waitcnt lgkmcnt(0)" ::: "memory"); SBAR();
;     ...
;   od = __builtin_amdgcn_mfma_f32_32x32x16_bf16(pa0, PK(l0, h0), od, 0, 0, 0);
;   od = __builtin_amdgcn_mfma_f32_32x32x16_bf16(pa1, PK(l1, h1), od, 0, 0, 0);
;   od = __builtin_amdgcn_mfma_f32_32x32x16_bf16(pa2, PK(l2, h2), od, 0, 0, 0);
;   od = __builtin_amdgcn_mfma_f32_32x32x16_bf16(pa3, PK(l3, h3), od, 0, 0, 0);
;     ...
; }
; __device__ __forceinline__ void pv_d0(f32x16* o, int vb, bf16x8 pa0, bf16x8 pa1, bf16x8 pa2, bf16x8 pa3) {
;   pv_one<0>(o[0], vb, pa0, pa1, pa2, pa3); pv_one<1>(o[1], vb, pa0, pa1, pa2, pa3); pv_one<2>(o[2], vb, pa0, pa1, pa2, pa3); pv_one<3>(o[3], vb, pa0, pa1, pa2, pa3);
	v_mfma_f32_32x32x16_bf16 v[34:49], v[138:141], v[226:229], v[34:49]
	ds_read_b64_tr_b16 v[226:227], v211 offset:0x600
	ds_read_b64_tr_b16 v[228:229], v211 offset:0xe00
	v_mfma_f32_32x32x16_bf16 v[34:49], v[222:225], v[230:233], v[34:49]
	ds_read_b64_tr_b16 v[230:231], v211 offset:0x1600
	ds_read_b64_tr_b16 v[232:233], v211 offset:0x1e00
	s_waitcnt lgkmcnt(4)
	v_mfma_f32_32x32x16_bf16 v[34:49], v[144:147], v[234:237], v[34:49]
	ds_read_b64_tr_b16 v[234:235], v211 offset:0x2600
	ds_read_b64_tr_b16 v[236:237], v211 offset:0x2e00
	v_mfma_f32_32x32x16_bf16 v[34:49], v[148:151], v[238:241], v[34:49]
	ds_read_b64_tr_b16 v[238:239], v211 offset:0x3600
	ds_read_b64_tr_b16 v[240:241], v211 offset:0x3e00
	s_waitcnt lgkmcnt(6)
	v_mfma_f32_32x32x16_bf16 v[18:33], v[138:141], v[226:229], v[18:33]
	v_max_f32_e32 v138, v83, v82
	v_max3_f32 v138, v138, v84, v85
	v_max3_f32 v138, v138, v86, v87
	v_max3_f32 v138, v138, v88, v89
	v_max3_f32 v138, v138, v90, v91
	v_max3_f32 v138, v138, v92, v93
	v_max3_f32 v138, v138, v94, v95
	s_waitcnt lgkmcnt(4)
	v_mfma_f32_32x32x16_bf16 v[18:33], v[222:225], v[230:233], v[18:33]
	v_max3_f32 v138, v138, v96, v97
	v_max3_f32 v138, v138, v66, v67
	v_max3_f32 v138, v138, v68, v69
	v_max3_f32 v138, v138, v70, v71
	v_max3_f32 v138, v138, v72, v73
	v_max3_f32 v138, v138, v74, v75
	v_max3_f32 v138, v138, v76, v77
	v_max3_f32 v138, v138, v78, v79
	s_waitcnt lgkmcnt(2)
	v_mfma_f32_32x32x16_bf16 v[18:33], v[144:147], v[234:237], v[18:33]
	v_max3_f32 v138, v138, v80, v81
	v_mov_b32_e32 v139, v138
	s_nop 1
	v_permlane32_swap_b32_e32 v138, v139
	v_max_f32_e32 v138, v139, v138
	v_sub_f32_e32 v139, v138, v142
	s_mov_b32 s2, 0x42800000
	v_cmp_ge_f32_e32 vcc, s2, v139
	v_max_f32_e32 v138, v142, v138
	s_waitcnt lgkmcnt(0)
	v_mfma_f32_32x32x16_bf16 v[18:33], v[148:151], v[238:241], v[18:33]
	v_sub_f32_e32 v139, v142, v138
	v_mul_f32_e32 v139, 0x3e38aa3b, v139
	v_exp_f32_e32 v139, v139
	s_cmp_eq_u64 vcc, exec
	s_cselect_b64 s[2:3], -1, 0
	s_waitcnt vmcnt(3)
	v_cndmask_b32_e64 v222, v139, 1.0, s[2:3]
	v_cmp_gt_f32_e32 vcc, 1.0, v222
	ds_write_b128 v214, v[122:125] offset:32768
	s_cbranch_vccz .LBB0_705
	s_and_saveexec_b64 s[4:5], s[0:1]
	ds_write_b32 v208, v222 offset:128
	s_or_b64 exec, exec, s[4:5]
	s_waitcnt lgkmcnt(0)
	v_add_u32_e32 v139, v207, v0
	ds_read_b128 v[144:147], v139 offset:224
	ds_read_b128 v[148:151], v139 offset:192
	ds_read_b128 v[224:227], v139 offset:160
	ds_read_b128 v[228:231], v139 offset:128
	s_waitcnt lgkmcnt(3)
	v_pk_mul_f32 v[14:15], v[14:15], v[144:145]
	s_waitcnt lgkmcnt(2)
	v_pk_mul_f32 v[10:11], v[10:11], v[148:149]
	s_waitcnt lgkmcnt(1)
	v_pk_mul_f32 v[6:7], v[6:7], v[224:225]
	v_pk_mul_f32 v[16:17], v[16:17], v[146:147]
	v_pk_mul_f32 v[12:13], v[12:13], v[150:151]
	v_pk_mul_f32 v[8:9], v[8:9], v[226:227]
	s_waitcnt lgkmcnt(0)
	v_pk_mul_f32 v[4:5], v[4:5], v[230:231]
	v_pk_mul_f32 v[2:3], v[2:3], v[228:229]
	v_pk_mul_f32 v[62:63], v[144:145], v[62:63]
	v_pk_mul_f32 v[58:59], v[148:149], v[58:59]
	v_pk_mul_f32 v[54:55], v[224:225], v[54:55]
	v_pk_mul_f32 v[64:65], v[146:147], v[64:65]
	v_pk_mul_f32 v[60:61], v[150:151], v[60:61]
	v_pk_mul_f32 v[56:57], v[226:227], v[56:57]
	v_pk_mul_f32 v[52:53], v[230:231], v[52:53]
	v_pk_mul_f32 v[50:51], v[228:229], v[50:51]
	v_pk_mul_f32 v[46:47], v[144:145], v[46:47]
	v_pk_mul_f32 v[42:43], v[148:149], v[42:43]
	v_pk_mul_f32 v[38:39], v[224:225], v[38:39]
	v_pk_mul_f32 v[48:49], v[146:147], v[48:49]
	v_pk_mul_f32 v[44:45], v[150:151], v[44:45]
	v_pk_mul_f32 v[40:41], v[226:227], v[40:41]
	v_pk_mul_f32 v[36:37], v[230:231], v[36:37]
	v_pk_mul_f32 v[34:35], v[228:229], v[34:35]
	v_pk_mul_f32 v[30:31], v[144:145], v[30:31]
	v_pk_mul_f32 v[26:27], v[148:149], v[26:27]
	v_pk_mul_f32 v[22:23], v[224:225], v[22:23]
	v_pk_mul_f32 v[32:33], v[146:147], v[32:33]
	v_pk_mul_f32 v[28:29], v[150:151], v[28:29]
	v_pk_mul_f32 v[24:25], v[226:227], v[24:25]
	v_pk_mul_f32 v[20:21], v[230:231], v[20:21]
	v_pk_mul_f32 v[18:19], v[228:229], v[18:19]
.LBB0_705:
	v_cndmask_b32_e64 v223, v138, v142, s[2:3]
	v_mul_f32_e32 v224, 0xbe38aa3b, v223
	v_fmamk_f32 v82, v82, 0x3e38aa3b, v224
	v_fmamk_f32 v83, v83, 0x3e38aa3b, v224
	v_fmamk_f32 v84, v84, 0x3e38aa3b, v224
	v_fmamk_f32 v85, v85, 0x3e38aa3b, v224
	v_fmamk_f32 v86, v86, 0x3e38aa3b, v224
	v_fmamk_f32 v87, v87, 0x3e38aa3b, v224
	v_fmamk_f32 v88, v88, 0x3e38aa3b, v224
	v_fmamk_f32 v89, v89, 0x3e38aa3b, v224
	v_fmamk_f32 v90, v90, 0x3e38aa3b, v224
	v_fmamk_f32 v91, v91, 0x3e38aa3b, v224
	v_fmamk_f32 v92, v92, 0x3e38aa3b, v224
	v_fmamk_f32 v93, v93, 0x3e38aa3b, v224
	v_fmamk_f32 v94, v94, 0x3e38aa3b, v224
	v_fmamk_f32 v95, v95, 0x3e38aa3b, v224
	v_fmamk_f32 v96, v96, 0x3e38aa3b, v224
	v_fmamk_f32 v97, v97, 0x3e38aa3b, v224
	v_exp_f32_e32 v138, v82
	v_exp_f32_e32 v153, v83
	v_exp_f32_e32 v139, v84
	v_exp_f32_e32 v152, v85
	v_exp_f32_e32 v140, v86
	v_exp_f32_e32 v151, v87
	v_exp_f32_e32 v141, v88
	v_exp_f32_e32 v150, v89
	v_exp_f32_e32 v142, v90
	v_exp_f32_e32 v149, v91
	v_exp_f32_e32 v143, v92
	v_exp_f32_e32 v148, v93
	v_exp_f32_e32 v144, v94
	v_exp_f32_e32 v147, v95
	v_exp_f32_e32 v145, v96
	v_exp_f32_e32 v146, v97
	v_fmamk_f32 v233, v66, 0x3e38aa3b, v224
	v_fmamk_f32 v234, v67, 0x3e38aa3b, v224
	v_fmamk_f32 v235, v68, 0x3e38aa3b, v224
	v_fmamk_f32 v236, v69, 0x3e38aa3b, v224
	v_fmamk_f32 v237, v70, 0x3e38aa3b, v224
	v_fmamk_f32 v226, v71, 0x3e38aa3b, v224
	v_fmamk_f32 v227, v72, 0x3e38aa3b, v224
	v_fmamk_f32 v228, v73, 0x3e38aa3b, v224
	v_fmamk_f32 v229, v74, 0x3e38aa3b, v224
	v_fmamk_f32 v230, v75, 0x3e38aa3b, v224
	v_fmamk_f32 v231, v76, 0x3e38aa3b, v224
	v_fmamk_f32 v232, v77, 0x3e38aa3b, v224
	v_fmamk_f32 v225, v78, 0x3e38aa3b, v224
	v_fmamk_f32 v238, v79, 0x3e38aa3b, v224
	v_fmamk_f32 v239, v80, 0x3e38aa3b, v224
	v_fmac_f32_e32 v224, 0x3e38aa3b, v81
	s_waitcnt lgkmcnt(0)
	s_barrier
; #define SBAR() __builtin_amdgcn_sched_barrier(0)
; #define SLOAD(i, k0) do { sr_[i].vs0 = *reinterpret_cast<const bf16x8*>(&Vh[(long)((k0) + sr) * LDP + sc]); sr_[i].vs1 = *reinterpret_cast<const bf16x8*>(&Vh[(long)((k0) + 32 + sr) * LDP + sc]); \
;     sr_[i].ks0 = *reinterpret_cast<const bf16x8*>(&Kh[(long)((k0) + ksr) * LDP + ksc]); if (DK == 128) sr_[i].ks1 = *reinterpret_cast<const bf16x8*>(&Kh[(long)((k0) + 32 + ksr) * LDP + ksc]); } while (0)
; #define HOOK(P0, P1, j) do { if (NA) na_hook(P0, P1, krow0 + (j), q_row, q_col, win_r, win_c, rpb, inv_scale, hi); } while (0)
; __device__ __forceinline__ void finishSM(f32x16& p0, f32x16& p1, float alpha, float& l_reg, bf16x8& pa0, bf16x8& pa1, bf16x8& pa2, bf16x8& pa3) {
; #pragma unroll
;   for (int r = 0; r < 16; ++r) p1[r] = __builtin_amdgcn_exp2f(p1[r]);
;   float ps = 0;
; #pragma unroll
;   for (int r = 0; r < 16; ++r) ps += p0[r];
; #pragma unroll
;   for (int r = 0; r < 16; ++r) ps += p1[r];
;   { auto rr = __builtin_amdgcn_permlane32_swap(__float_as_uint(ps), __float_as_uint(ps), false, false);
;     ps = __uint_as_float(rr[0]) + __uint_as_float(rr[1]); }
;   l_reg = l_reg * alpha + ps;
;     ...
;   PK4(p0, 0, pa0); PK4(p0, 8, pa1); PK4(p1, 0, pa2); PK4(p1, 8, pa3);
;     ...
; }
; template <int DK, bool QL>
; __device__ __forceinline__ void qkt(f32x16& p0, f32x16& p1, const bf16* Ks, const bf16x8* qr, const char* ql, int r32, int hi) {
;   p0 = f32x16{}; p1 = f32x16{};
; #pragma unroll
;   for (int d0 = 0; d0 < DK / 16; ++d0) { int cb = (d0 * 16 + hi * 8) * 2;
;     const bf16x8 qv = QL ? *reinterpret_cast<const bf16x8*>(ql + d0 * 1024) : qr[d0];
;     bf16x8 b0 = *reinterpret_cast<const bf16x8*>((const char*)Ks + kswz<DK>(r32, cb));
;     bf16x8 b1 = *reinterpret_cast<const bf16x8*>((const char*)Ks + kswz<DK>(32 + r32, cb));
;     p0 = __builtin_amdgcn_mfma_f32_32x32x16_bf16(b0, qv, p0, 0, 0, 0);
;     p1 = __builtin_amdgcn_mfma_f32_32x32x16_bf16(b1, qv, p1, 0, 0, 0); }
; template <int DK, bool NA, bool QL, int SD> ...
;     ...
;     SBAR(); qkt<DK, QL>(pA0, pA1, K_lds, qr, ql, r32, hi); HOOK(pA0, pA1, j + 1);
;     finishSM(pB0, pB1, alB, l_reg, pa0, pa1, pa2, pa3); SBAR();
;     if (SD == 1 || j + 3 < NT) SLOAD(SE, (j + 1 + SD) * KVBLK); SBAR();
	ds_write_b128 v212, v[114:117]
	ds_write_b128 v213, v[118:121]
	ds_read_b128 v[66:69], v215 offset:32768
	ds_read_b128 v[70:73], v215 offset:36864
	v_exp_f32_e32 v164, v233
	v_exp_f32_e32 v233, v224
	v_add_f32_e32 v224, v153, v138
	s_waitcnt lgkmcnt(1)
	v_mfma_f32_32x32x16_bf16 v[82:97], v[66:69], v[110:113], 0
	v_add_f32_e32 v224, v139, v224
	v_add_f32_e32 v224, v152, v224
	v_add_f32_e32 v224, v140, v224
	ds_read_b128 v[240:243], v216 offset:32768
	ds_read_b128 v[244:247], v216 offset:36864
	v_add_f32_e32 v224, v151, v224
	v_add_f32_e32 v224, v141, v224
	v_add_f32_e32 v224, v150, v224
	s_waitcnt lgkmcnt(2)
	v_mfma_f32_32x32x16_bf16 v[66:81], v[70:73], v[110:113], 0
	v_add_f32_e32 v224, v142, v224
	v_add_f32_e32 v224, v149, v224
	v_add_f32_e32 v224, v143, v224
	v_add_f32_e32 v224, v148, v224
	v_add_f32_e32 v224, v144, v224
	v_exp_f32_e32 v165, v234
	v_add_f32_e32 v224, v147, v224
	s_waitcnt lgkmcnt(1)
	v_mfma_f32_32x32x16_bf16 v[82:97], v[240:243], v[106:109], v[82:97]
	v_exp_f32_e32 v166, v235
	v_add_f32_e32 v224, v145, v224
	v_exp_f32_e32 v167, v236
	v_add_f32_e32 v224, v146, v224
	v_exp_f32_e32 v172, v237
	v_add_f32_e32 v224, v164, v224
	v_exp_f32_e32 v173, v226
	s_waitcnt lgkmcnt(0)
	v_mfma_f32_32x32x16_bf16 v[66:81], v[244:247], v[106:109], v[66:81]
	ds_read_b128 v[240:243], v217 offset:32768
	ds_read_b128 v[244:247], v217 offset:36864
	v_add_f32_e32 v224, v165, v224
	v_exp_f32_e32 v174, v227
	v_add_f32_e32 v224, v166, v224
	v_exp_f32_e32 v175, v228
	v_add_f32_e32 v224, v167, v224
	v_exp_f32_e32 v226, v229
	s_waitcnt lgkmcnt(1)
	v_mfma_f32_32x32x16_bf16 v[82:97], v[240:243], v[102:105], v[82:97]
	v_add_f32_e32 v224, v172, v224
	v_exp_f32_e32 v227, v230
	v_add_f32_e32 v224, v173, v224
	v_exp_f32_e32 v228, v231
	v_add_f32_e32 v224, v174, v224
	v_exp_f32_e32 v229, v232
	v_add_f32_e32 v224, v175, v224
	s_waitcnt lgkmcnt(0)
	v_mfma_f32_32x32x16_bf16 v[66:81], v[244:247], v[102:105], v[66:81]
	ds_read_b128 v[240:243], v218 offset:32768
	ds_read_b128 v[244:247], v218 offset:36864
	v_exp_f32_e32 v230, v225
	v_add_f32_e32 v224, v226, v224
	v_exp_f32_e32 v231, v238
	v_add_f32_e32 v224, v227, v224
	v_exp_f32_e32 v232, v239
	v_add_f32_e32 v224, v228, v224
	s_waitcnt lgkmcnt(1)
	v_mfma_f32_32x32x16_bf16 v[82:97], v[240:243], v[98:101], v[82:97]
	v_add_f32_e32 v224, v229, v224
	v_add_f32_e32 v224, v230, v224
	v_add_f32_e32 v224, v231, v224
	v_add_f32_e32 v224, v232, v224
	v_add_f32_e32 v224, v233, v224
	v_mov_b32_e32 v225, v224
	v_cvt_pk_bf16_f32 v138, v138, v153
	s_waitcnt lgkmcnt(0)
	v_mfma_f32_32x32x16_bf16 v[66:81], v[244:247], v[98:101], v[66:81]
	v_cvt_pk_bf16_f32 v139, v139, v152
	v_cvt_pk_bf16_f32 v140, v140, v151
	v_cvt_pk_bf16_f32 v141, v141, v150
	v_cvt_pk_bf16_f32 v142, v142, v149
	v_cvt_pk_bf16_f32 v143, v143, v148
	v_cvt_pk_bf16_f32 v144, v144, v147
	v_cvt_pk_bf16_f32 v145, v145, v146
	v_cvt_pk_bf16_f32 v146, v164, v165
	v_cvt_pk_bf16_f32 v147, v166, v167
	v_cvt_pk_bf16_f32 v148, v172, v173
	v_cvt_pk_bf16_f32 v149, v174, v175
	v_cvt_pk_bf16_f32 v150, v226, v227
	v_cvt_pk_bf16_f32 v151, v228, v229
	v_cvt_pk_bf16_f32 v152, v230, v231
	v_cvt_pk_bf16_f32 v153, v232, v233
	v_permlane32_swap_b32_e32 v224, v225
	v_permlane32_swap_b32_e32 v138, v140
	v_permlane32_swap_b32_e32 v139, v141
	v_permlane32_swap_b32_e32 v142, v144
	v_permlane32_swap_b32_e32 v143, v145
	v_permlane32_swap_b32_e32 v146, v148
	v_permlane32_swap_b32_e32 v147, v149
	v_permlane32_swap_b32_e32 v150, v152
	v_permlane32_swap_b32_e32 v151, v153
	s_cmp_gt_u32 s8, 60
	s_cselect_b64 s[4:5], -1, 0
	s_and_b64 vcc, exec, s[4:5]
	s_cbranch_vccnz .Lod_d2
	global_load_dwordx4 v[114:117], v[178:179], off offset:2048
	global_load_dwordx4 v[118:121], v[180:181], off offset:2048
	global_load_dwordx4 v[122:125], v[204:205], off offset:1152
	s_mov_b32 s6, 0xa0000
	s_mov_b32 s7, 0
	s_nop 0
	v_lshl_add_u64 v[178:179], v[178:179], 0, s[6:7]
	v_lshl_add_u64 v[180:181], v[180:181], 0, s[6:7]
	v_lshl_add_u64 v[204:205], v[204:205], 0, s[6:7]
; #define SBAR() __builtin_amdgcn_sched_barrier(0)
; #define SWAIT() do { if (SD == 1) asm volatile("s_waitcnt vmcnt(0)" ::: "memory"); else if (DK == 128) asm volatile("s_waitcnt vmcnt(4)" ::: "memory"); else asm volatile("s_waitcnt vmcnt(3)" ::: "memory"); } while (0)
; #define RESC(a) do { if (__any((a) < 1.f)) { if (hi == 0) al_l[r32] = (a); asm volatile("s_waitcnt lgkmcnt(0)" ::: "memory"); \
;     _Pragma("unroll") for (int d = 0; d < 4; ++d) _Pragma("unroll") for (int r = 0; r < 16; ++r) o[d][r] *= al_l[crow(r, hi)]; } } while (0)
; template <int D0> __device__ __forceinline__ void pv_one(f32x16& od, int vb, bf16x8 pa0, bf16x8 pa1, bf16x8 pa2, bf16x8 pa3) {
;   const s16x4 l0 = tr_read<v_rd_off(D0, 0, 0)>(vb), h0 = tr_read<v_rd_off(D0, 0, 1)>(vb), l1 = tr_read<v_rd_off(D0, 1, 0)>(vb), h1 = tr_read<v_rd_off(D0, 1, 1)>(vb);
;   const s16x4 l2 = tr_read<v_rd_off(D0, 2, 0)>(vb), h2 = tr_read<v_rd_off(D0, 2, 1)>(vb), l3 = tr_read<v_rd_off(D0, 3, 0)>(vb), h3 = tr_read<v_rd_off(D0, 3, 1)>(vb);
;   asm volatile("s_waitcnt lgkmcnt(0)" ::: "memory"); SBAR();
;     ...
;   od = __builtin_amdgcn_mfma_f32_32x32x16_bf16(pa0, PK(l0, h0), od, 0, 0, 0);
;   od = __builtin_amdgcn_mfma_f32_32x32x16_bf16(pa1, PK(l1, h1), od, 0, 0, 0);
;   od = __builtin_amdgcn_mfma_f32_32x32x16_bf16(pa2, PK(l2, h2), od, 0, 0, 0);
;   od = __builtin_amdgcn_mfma_f32_32x32x16_bf16(pa3, PK(l3, h3), od, 0, 0, 0);
;     ...
; }
; __device__ __forceinline__ void pv_d0(f32x16* o, int vb, bf16x8 pa0, bf16x8 pa1, bf16x8 pa2, bf16x8 pa3) {
;   pv_one<0>(o[0], vb, pa0, pa1, pa2, pa3); pv_one<1>(o[1], vb, pa0, pa1, pa2, pa3); pv_one<2>(o[2], vb, pa0, pa1, pa2, pa3); pv_one<3>(o[3], vb, pa0, pa1, pa2, pa3);
; template <int DK, bool NA, bool QL, int SD> ...
;     ...
;     pv_d0(o, vb0 + (int)SHM_V, pa0, pa1, pa2, pa3); partialSM(pA0, pA1, m_reg, mnA, alA, C, thrRaw);
;     __syncthreads(); SWAIT(); SWRITE(1, SO);
;     RESC(alA); __syncthreads();
.LBB0_707:
	ds_read_b64_tr_b16 v[226:227], v210 offset:0
	ds_read_b64_tr_b16 v[228:229], v210 offset:0x800
	ds_read_b64_tr_b16 v[230:231], v210 offset:0x1000
	ds_read_b64_tr_b16 v[232:233], v210 offset:0x1800
	ds_read_b64_tr_b16 v[234:235], v210 offset:0x2000
	ds_read_b64_tr_b16 v[236:237], v210 offset:0x2800
	ds_read_b64_tr_b16 v[238:239], v210 offset:0x3000
	ds_read_b64_tr_b16 v[240:241], v210 offset:0x3800
	s_waitcnt lgkmcnt(4)
	s_nop 0
	v_mfma_f32_32x32x16_bf16 v[2:17], v[138:141], v[226:229], v[2:17]
	ds_read_b64_tr_b16 v[226:227], v210 offset:0x200
	ds_read_b64_tr_b16 v[228:229], v210 offset:0xa00
	v_mfma_f32_32x32x16_bf16 v[2:17], v[142:145], v[230:233], v[2:17]
	ds_read_b64_tr_b16 v[230:231], v210 offset:0x1200
	ds_read_b64_tr_b16 v[232:233], v210 offset:0x1a00
	s_waitcnt lgkmcnt(4)
	v_mfma_f32_32x32x16_bf16 v[2:17], v[146:149], v[234:237], v[2:17]
	ds_read_b64_tr_b16 v[234:235], v210 offset:0x2200
	ds_read_b64_tr_b16 v[236:237], v210 offset:0x2a00
	v_mfma_f32_32x32x16_bf16 v[2:17], v[150:153], v[238:241], v[2:17]
	ds_read_b64_tr_b16 v[238:239], v210 offset:0x3200
	ds_read_b64_tr_b16 v[240:241], v210 offset:0x3a00
	s_waitcnt lgkmcnt(4)
	v_mfma_f32_32x32x16_bf16 v[50:65], v[138:141], v[226:229], v[50:65]
	ds_read_b64_tr_b16 v[226:227], v210 offset:0x400
	ds_read_b64_tr_b16 v[228:229], v210 offset:0xc00
	v_mfma_f32_32x32x16_bf16 v[50:65], v[142:145], v[230:233], v[50:65]
	ds_read_b64_tr_b16 v[230:231], v210 offset:0x1400
	ds_read_b64_tr_b16 v[232:233], v210 offset:0x1c00
	s_waitcnt lgkmcnt(4)
	v_mfma_f32_32x32x16_bf16 v[50:65], v[146:149], v[234:237], v[50:65]
	ds_read_b64_tr_b16 v[234:235], v210 offset:0x2400
	ds_read_b64_tr_b16 v[236:237], v210 offset:0x2c00
	v_mfma_f32_32x32x16_bf16 v[50:65], v[150:153], v[238:241], v[50:65]
	ds_read_b64_tr_b16 v[238:239], v210 offset:0x3400
	ds_read_b64_tr_b16 v[240:241], v210 offset:0x3c00
	s_waitcnt lgkmcnt(4)
	v_mfma_f32_32x32x16_bf16 v[34:49], v[138:141], v[226:229], v[34:49]
	ds_read_b64_tr_b16 v[226:227], v210 offset:0x600
	ds_read_b64_tr_b16 v[228:229], v210 offset:0xe00
	v_mfma_f32_32x32x16_bf16 v[34:49], v[142:145], v[230:233], v[34:49]
	ds_read_b64_tr_b16 v[230:231], v210 offset:0x1600
	ds_read_b64_tr_b16 v[232:233], v210 offset:0x1e00
	s_waitcnt lgkmcnt(4)
	v_mfma_f32_32x32x16_bf16 v[34:49], v[146:149], v[234:237], v[34:49]
	ds_read_b64_tr_b16 v[234:235], v210 offset:0x2600
	ds_read_b64_tr_b16 v[236:237], v210 offset:0x2e00
	v_mfma_f32_32x32x16_bf16 v[34:49], v[150:153], v[238:241], v[34:49]
	ds_read_b64_tr_b16 v[238:239], v210 offset:0x3600
	ds_read_b64_tr_b16 v[240:241], v210 offset:0x3e00
	s_waitcnt lgkmcnt(6)
	v_mfma_f32_32x32x16_bf16 v[18:33], v[138:141], v[226:229], v[18:33]
	v_max_f32_e32 v138, v83, v82
	v_max3_f32 v138, v138, v84, v85
	v_max3_f32 v138, v138, v86, v87
	v_max3_f32 v138, v138, v88, v89
	v_max3_f32 v138, v138, v90, v91
	v_max3_f32 v138, v138, v92, v93
	v_max3_f32 v138, v138, v94, v95
	s_waitcnt lgkmcnt(4)
	v_mfma_f32_32x32x16_bf16 v[18:33], v[142:145], v[230:233], v[18:33]
	v_max3_f32 v138, v138, v96, v97
	v_max3_f32 v138, v138, v66, v67
	v_max3_f32 v138, v138, v68, v69
	v_max3_f32 v138, v138, v70, v71
	v_max3_f32 v138, v138, v72, v73
	v_max3_f32 v138, v138, v74, v75
	v_max3_f32 v138, v138, v76, v77
	v_max3_f32 v138, v138, v78, v79
	s_waitcnt lgkmcnt(2)
	v_mfma_f32_32x32x16_bf16 v[18:33], v[146:149], v[234:237], v[18:33]
	v_max3_f32 v138, v138, v80, v81
	v_mov_b32_e32 v139, v138
	s_nop 1
	v_permlane32_swap_b32_e32 v138, v139
	v_max_f32_e32 v138, v139, v138
	v_sub_f32_e32 v139, v138, v223
	s_mov_b32 s2, 0x42800000
	v_cmp_ge_f32_e32 vcc, s2, v139
	v_max_f32_e32 v138, v223, v138
	s_waitcnt lgkmcnt(0)
	v_mfma_f32_32x32x16_bf16 v[18:33], v[150:153], v[238:241], v[18:33]
	v_sub_f32_e32 v139, v223, v138
	v_mul_f32_e32 v139, 0x3e38aa3b, v139
	v_exp_f32_e32 v139, v139
	s_cmp_eq_u64 vcc, exec
	s_cselect_b64 s[2:3], -1, 0
	s_waitcnt vmcnt(3)
	v_cndmask_b32_e64 v143, v139, 1.0, s[2:3]
	v_cmp_gt_f32_e32 vcc, 1.0, v143
	ds_write_b128 v214, v[134:137] offset:49152
	s_cbranch_vccz .LBB0_711
	s_and_saveexec_b64 s[6:7], s[0:1]
	ds_write_b32 v208, v143 offset:128
	s_or_b64 exec, exec, s[6:7]
	s_waitcnt lgkmcnt(0)
	v_add_u32_e32 v139, v207, v0
	ds_read_b128 v[126:129], v139 offset:224
	ds_read_b128 v[130:133], v139 offset:192
	ds_read_b128 v[134:137], v139 offset:160
	ds_read_b128 v[144:147], v139 offset:128
	s_waitcnt lgkmcnt(3)
	v_pk_mul_f32 v[14:15], v[14:15], v[126:127]
	s_waitcnt lgkmcnt(2)
	v_pk_mul_f32 v[10:11], v[10:11], v[130:131]
	s_waitcnt lgkmcnt(1)
	v_pk_mul_f32 v[6:7], v[6:7], v[134:135]
	v_pk_mul_f32 v[16:17], v[16:17], v[128:129]
	v_pk_mul_f32 v[12:13], v[12:13], v[132:133]
	v_pk_mul_f32 v[8:9], v[8:9], v[136:137]
	s_waitcnt lgkmcnt(0)
	v_pk_mul_f32 v[4:5], v[4:5], v[146:147]
	v_pk_mul_f32 v[2:3], v[2:3], v[144:145]
	v_pk_mul_f32 v[62:63], v[126:127], v[62:63]
	v_pk_mul_f32 v[58:59], v[130:131], v[58:59]
	v_pk_mul_f32 v[54:55], v[134:135], v[54:55]
	v_pk_mul_f32 v[64:65], v[128:129], v[64:65]
	v_pk_mul_f32 v[60:61], v[132:133], v[60:61]
	v_pk_mul_f32 v[56:57], v[136:137], v[56:57]
	v_pk_mul_f32 v[52:53], v[146:147], v[52:53]
	v_pk_mul_f32 v[50:51], v[144:145], v[50:51]
	v_pk_mul_f32 v[46:47], v[126:127], v[46:47]
	v_pk_mul_f32 v[42:43], v[130:131], v[42:43]
	v_pk_mul_f32 v[38:39], v[134:135], v[38:39]
	v_pk_mul_f32 v[48:49], v[128:129], v[48:49]
	v_pk_mul_f32 v[44:45], v[132:133], v[44:45]
	v_pk_mul_f32 v[40:41], v[136:137], v[40:41]
	v_pk_mul_f32 v[36:37], v[146:147], v[36:37]
	v_pk_mul_f32 v[34:35], v[144:145], v[34:35]
	v_pk_mul_f32 v[30:31], v[126:127], v[30:31]
	v_pk_mul_f32 v[26:27], v[130:131], v[26:27]
	v_pk_mul_f32 v[22:23], v[134:135], v[22:23]
	v_pk_mul_f32 v[32:33], v[128:129], v[32:33]
	v_pk_mul_f32 v[28:29], v[132:133], v[28:29]
	v_pk_mul_f32 v[24:25], v[136:137], v[24:25]
	v_pk_mul_f32 v[20:21], v[146:147], v[20:21]
	v_pk_mul_f32 v[18:19], v[144:145], v[18:19]
